# silu in the P2/P7 in-projection epilogues computed as v*rcp(1+exp2(-v*log2e)) in f32 (v_rcp_f32) instead of the 11-instruction IEEE divide sequence
# speedup vs baseline: 1.0059x; 1.0059x over previous
; __device__ __forceinline__ unsigned cvt_pk_bf16(float lo, float hi) { unsigned r; asm volatile("v_cvt_pk_bf16_f32 %0, %1, %2" : "=v"(r) : "v"(lo), "v"(hi)); return r; }
; __device__ __forceinline__ float silu_f(float v) { return v / (1.0f + __expf(-v)); }
; __device__ __forceinline__ void st8(bf16_t* p, f32x4 v0, f32x4 v1) {
;     u32x4 w; w.x = cvt_pk_bf16(v0[0], v0[1]); w.y = cvt_pk_bf16(v0[2], v0[3]); w.z = cvt_pk_bf16(v1[0], v1[1]); w.w = cvt_pk_bf16(v1[2], v1[3]);
;     *(u32x4*)p = w;
; }
; __device__ __forceinline__ f32x4 silu4(f32x4 v) { f32x4 o; o[0] = silu_f(v[0]); o[1] = silu_f(v[1]); o[2] = silu_f(v[2]); o[3] = silu_f(v[3]); return o; }
;     __device__ __forceinline__ void operator()(const f32x4 (&acc)[2][2][4][2], const Unit& u, int wr, int wc, int fr, int fq) const {
;     ...
;             const bool isg = u.pn >= 32; bf16_t* base = (isg ? SG + (u.pn - 32) * 256 : V + (u.pn - 16) * 256) + cl;
; #pragma unroll
;             for (int ai = 0; ai < 2; ++ai)
; #pragma unroll
;                 for (int m = 0; m < 4; ++m) { bf16_t* rowp = base + (size_t)(row0 + ai * HALF + m * 16) * 4096;
; #pragma unroll
;                     for (int bj = 0; bj < 2; ++bj) { f32x4 v0 = acc[ai][bj][m][0], v1 = acc[ai][bj][m][1];
;                         if (isg) { v0 = silu4(v0); v1 = silu4(v1); }
;                         st8(rowp + bj * HALF, v0, v1); } }
.LBB0_303:
	s_cmp_gt_u32 s0, 31
	s_cselect_b64 s[36:37], -1, 0
	s_cmp_lt_u32 s0, 32
	v_mov_b32_e32 v163, v123
	v_mov_b32_e32 v162, v122
	v_mov_b32_e32 v161, v121
	v_mov_b32_e32 v160, v120
	v_mov_b32_e32 v135, v127
	v_mov_b32_e32 v134, v126
	v_mov_b32_e32 v133, v125
	v_mov_b32_e32 v132, v124
	s_cbranch_scc1 .LBB0_305
	v_mul_f32_e32 v163, 0xbfb8aa3b, v123
	v_mul_f32_e32 v162, 0xbfb8aa3b, v122
	v_mul_f32_e32 v161, 0xbfb8aa3b, v121
	v_mul_f32_e32 v160, 0xbfb8aa3b, v120
	v_mul_f32_e32 v135, 0xbfb8aa3b, v127
	v_mul_f32_e32 v134, 0xbfb8aa3b, v126
	v_mul_f32_e32 v133, 0xbfb8aa3b, v125
	v_mul_f32_e32 v132, 0xbfb8aa3b, v124
	v_exp_f32_e32 v163, v163
	v_exp_f32_e32 v162, v162
	v_exp_f32_e32 v161, v161
	v_exp_f32_e32 v160, v160
	v_exp_f32_e32 v135, v135
	v_exp_f32_e32 v134, v134
	v_exp_f32_e32 v133, v133
	v_exp_f32_e32 v132, v132
	v_add_f32_e32 v163, 1.0, v163
	v_add_f32_e32 v162, 1.0, v162
	v_add_f32_e32 v161, 1.0, v161
	v_add_f32_e32 v160, 1.0, v160
	v_add_f32_e32 v135, 1.0, v135
	v_add_f32_e32 v134, 1.0, v134
	v_add_f32_e32 v133, 1.0, v133
	v_add_f32_e32 v132, 1.0, v132
	v_rcp_f32_e32 v163, v163
	v_rcp_f32_e32 v162, v162
	v_rcp_f32_e32 v161, v161
	v_rcp_f32_e32 v160, v160
	v_rcp_f32_e32 v135, v135
	v_rcp_f32_e32 v134, v134
	v_rcp_f32_e32 v133, v133
	v_rcp_f32_e32 v132, v132
	v_mul_f32_e32 v163, v123, v163
	v_mul_f32_e32 v162, v122, v162
	v_mul_f32_e32 v161, v121, v161
	v_mul_f32_e32 v160, v120, v160
	v_mul_f32_e32 v135, v127, v135
	v_mul_f32_e32 v134, v126, v134
	v_mul_f32_e32 v133, v125, v133
	v_mul_f32_e32 v132, v124, v132
.LBB0_305:
	s_lshl_b32 s1, s0, 9
	s_add_u32 s1, s90, s1
	s_addc_u32 s4, s91, 0
	s_add_u32 s31, s1, 0x2dffc000
	s_addc_u32 s33, s4, 0
	s_add_u32 s1, s1, 0x1dffe000
	s_addc_u32 s35, s4, 0
	s_and_b64 s[4:5], s[36:37], exec
	s_cselect_b32 s5, s33, s35
	s_cselect_b32 s4, s31, s1
	v_lshlrev_b32_e32 v144, 1, v146
	v_ashrrev_i32_e32 v159, 31, v158
	v_lshl_add_u64 v[128:129], s[4:5], 0, v[144:145]
	v_lshlrev_b64 v[130:131], 13, v[158:159]
	v_lshl_add_u64 v[130:131], v[128:129], 0, v[130:131]
	v_cvt_pk_bf16_f32 v132, v132, v133
	v_cvt_pk_bf16_f32 v133, v134, v135
	v_cvt_pk_bf16_f32 v134, v160, v161
	v_cvt_pk_bf16_f32 v135, v162, v163
	global_store_dwordx4 v[130:131], v[132:135], off
	s_andn2_b64 vcc, exec, s[36:37]
	v_mov_b32_e32 v162, v115
	v_cndmask_b32_e64 v132, 0, 1, s[36:37]
	v_cmp_ne_u32_e64 s[4:5], 1, v132
	v_mov_b32_e32 v161, v114
	v_mov_b32_e32 v160, v113
	v_mov_b32_e32 v144, v112
	v_mov_b32_e32 v135, v119
	v_mov_b32_e32 v134, v118
	v_mov_b32_e32 v133, v117
	v_mov_b32_e32 v132, v116
	s_cbranch_vccnz .LBB0_307
	v_mul_f32_e32 v162, 0xbfb8aa3b, v115
	v_mul_f32_e32 v161, 0xbfb8aa3b, v114
	v_mul_f32_e32 v160, 0xbfb8aa3b, v113
	v_mul_f32_e32 v144, 0xbfb8aa3b, v112
	v_mul_f32_e32 v135, 0xbfb8aa3b, v119
	v_mul_f32_e32 v134, 0xbfb8aa3b, v118
	v_mul_f32_e32 v133, 0xbfb8aa3b, v117
	v_mul_f32_e32 v132, 0xbfb8aa3b, v116
	v_exp_f32_e32 v162, v162
	v_exp_f32_e32 v161, v161
	v_exp_f32_e32 v160, v160
	v_exp_f32_e32 v144, v144
	v_exp_f32_e32 v135, v135
	v_exp_f32_e32 v134, v134
	v_exp_f32_e32 v133, v133
	v_exp_f32_e32 v132, v132
	v_add_f32_e32 v162, 1.0, v162
	v_add_f32_e32 v161, 1.0, v161
	v_add_f32_e32 v160, 1.0, v160
	v_add_f32_e32 v144, 1.0, v144
	v_add_f32_e32 v135, 1.0, v135
	v_add_f32_e32 v134, 1.0, v134
	v_add_f32_e32 v133, 1.0, v133
	v_add_f32_e32 v132, 1.0, v132
	v_rcp_f32_e32 v162, v162
	v_rcp_f32_e32 v161, v161
	v_rcp_f32_e32 v160, v160
	v_rcp_f32_e32 v144, v144
	v_rcp_f32_e32 v135, v135
	v_rcp_f32_e32 v134, v134
	v_rcp_f32_e32 v133, v133
	v_rcp_f32_e32 v132, v132
	v_mul_f32_e32 v162, v115, v162
	v_mul_f32_e32 v161, v114, v161
	v_mul_f32_e32 v160, v113, v160
	v_mul_f32_e32 v144, v112, v144
	v_mul_f32_e32 v135, v119, v135
	v_mul_f32_e32 v134, v118, v134
	v_mul_f32_e32 v133, v117, v133
	v_mul_f32_e32 v132, v116, v132
.LBB0_307:
	v_cvt_pk_bf16_f32 v132, v132, v133
	v_cvt_pk_bf16_f32 v133, v134, v135
	v_cvt_pk_bf16_f32 v134, v144, v160
	v_cvt_pk_bf16_f32 v135, v161, v162
	global_store_dwordx4 v[130:131], v[132:135], off offset:256
	s_and_b64 vcc, exec, s[4:5]
	v_mov_b32_e32 v162, v107
	v_mov_b32_e32 v161, v106
	v_mov_b32_e32 v160, v105
	v_mov_b32_e32 v144, v104
	v_mov_b32_e32 v135, v111
	v_mov_b32_e32 v134, v110
	v_mov_b32_e32 v133, v109
	v_mov_b32_e32 v132, v108
	s_cbranch_vccnz .LBB0_309
	v_mul_f32_e32 v162, 0xbfb8aa3b, v107
	v_mul_f32_e32 v161, 0xbfb8aa3b, v106
	v_mul_f32_e32 v160, 0xbfb8aa3b, v105
	v_mul_f32_e32 v144, 0xbfb8aa3b, v104
	v_mul_f32_e32 v135, 0xbfb8aa3b, v111
	v_mul_f32_e32 v134, 0xbfb8aa3b, v110
	v_mul_f32_e32 v133, 0xbfb8aa3b, v109
	v_mul_f32_e32 v132, 0xbfb8aa3b, v108
	v_exp_f32_e32 v162, v162
	v_exp_f32_e32 v161, v161
	v_exp_f32_e32 v160, v160
	v_exp_f32_e32 v144, v144
	v_exp_f32_e32 v135, v135
	v_exp_f32_e32 v134, v134
	v_exp_f32_e32 v133, v133
	v_exp_f32_e32 v132, v132
	v_add_f32_e32 v162, 1.0, v162
	v_add_f32_e32 v161, 1.0, v161
	v_add_f32_e32 v160, 1.0, v160
	v_add_f32_e32 v144, 1.0, v144
	v_add_f32_e32 v135, 1.0, v135
	v_add_f32_e32 v134, 1.0, v134
	v_add_f32_e32 v133, 1.0, v133
	v_add_f32_e32 v132, 1.0, v132
	v_rcp_f32_e32 v162, v162
	v_rcp_f32_e32 v161, v161
	v_rcp_f32_e32 v160, v160
	v_rcp_f32_e32 v144, v144
	v_rcp_f32_e32 v135, v135
	v_rcp_f32_e32 v134, v134
	v_rcp_f32_e32 v133, v133
	v_rcp_f32_e32 v132, v132
	v_mul_f32_e32 v162, v107, v162
	v_mul_f32_e32 v161, v106, v161
	v_mul_f32_e32 v160, v105, v160
	v_mul_f32_e32 v144, v104, v144
	v_mul_f32_e32 v135, v111, v135
	v_mul_f32_e32 v134, v110, v134
	v_mul_f32_e32 v133, v109, v133
	v_mul_f32_e32 v132, v108, v132
; __device__ __forceinline__ unsigned cvt_pk_bf16(float lo, float hi) { unsigned r; asm volatile("v_cvt_pk_bf16_f32 %0, %1, %2" : "=v"(r) : "v"(lo), "v"(hi)); return r; }
; __device__ __forceinline__ float silu_f(float v) { return v / (1.0f + __expf(-v)); }
; __device__ __forceinline__ void st8(bf16_t* p, f32x4 v0, f32x4 v1) {
;     u32x4 w; w.x = cvt_pk_bf16(v0[0], v0[1]); w.y = cvt_pk_bf16(v0[2], v0[3]); w.z = cvt_pk_bf16(v1[0], v1[1]); w.w = cvt_pk_bf16(v1[2], v1[3]);
;     *(u32x4*)p = w;
; }
; __device__ __forceinline__ f32x4 silu4(f32x4 v) { f32x4 o; o[0] = silu_f(v[0]); o[1] = silu_f(v[1]); o[2] = silu_f(v[2]); o[3] = silu_f(v[3]); return o; }
;     __device__ __forceinline__ void operator()(const f32x4 (&acc)[2][2][4][2], const Unit& u, int wr, int wc, int fr, int fq) const {
;     ...
;             const bool isg = u.pn >= 32; bf16_t* base = (isg ? SG + (u.pn - 32) * 256 : V + (u.pn - 16) * 256) + cl;
; #pragma unroll
;             for (int ai = 0; ai < 2; ++ai)
; #pragma unroll
;                 for (int m = 0; m < 4; ++m) { bf16_t* rowp = base + (size_t)(row0 + ai * HALF + m * 16) * 4096;
; #pragma unroll
;                     for (int bj = 0; bj < 2; ++bj) { f32x4 v0 = acc[ai][bj][m][0], v1 = acc[ai][bj][m][1];
;                         if (isg) { v0 = silu4(v0); v1 = silu4(v1); }
;                         st8(rowp + bj * HALF, v0, v1); } }
.LBB0_309:
	v_or_b32_e32 v130, 16, v158
	v_ashrrev_i32_e32 v131, 31, v130
	v_lshlrev_b64 v[130:131], 13, v[130:131]
	v_lshl_add_u64 v[130:131], v[128:129], 0, v[130:131]
	v_cvt_pk_bf16_f32 v132, v132, v133
	v_cvt_pk_bf16_f32 v133, v134, v135
	v_cvt_pk_bf16_f32 v134, v144, v160
	v_cvt_pk_bf16_f32 v135, v161, v162
	global_store_dwordx4 v[130:131], v[132:135], off
	s_and_b64 vcc, exec, s[4:5]
	v_mov_b32_e32 v162, v99
	v_mov_b32_e32 v161, v98
	v_mov_b32_e32 v160, v97
	v_mov_b32_e32 v144, v96
	v_mov_b32_e32 v135, v103
	v_mov_b32_e32 v134, v102
	v_mov_b32_e32 v133, v101
	v_mov_b32_e32 v132, v100
	s_cbranch_vccnz .LBB0_311
	v_mul_f32_e32 v162, 0xbfb8aa3b, v99
	v_mul_f32_e32 v161, 0xbfb8aa3b, v98
	v_mul_f32_e32 v160, 0xbfb8aa3b, v97
	v_mul_f32_e32 v144, 0xbfb8aa3b, v96
	v_mul_f32_e32 v135, 0xbfb8aa3b, v103
	v_mul_f32_e32 v134, 0xbfb8aa3b, v102
	v_mul_f32_e32 v133, 0xbfb8aa3b, v101
	v_mul_f32_e32 v132, 0xbfb8aa3b, v100
	v_exp_f32_e32 v162, v162
	v_exp_f32_e32 v161, v161
	v_exp_f32_e32 v160, v160
	v_exp_f32_e32 v144, v144
	v_exp_f32_e32 v135, v135
	v_exp_f32_e32 v134, v134
	v_exp_f32_e32 v133, v133
	v_exp_f32_e32 v132, v132
	v_add_f32_e32 v162, 1.0, v162
	v_add_f32_e32 v161, 1.0, v161
	v_add_f32_e32 v160, 1.0, v160
	v_add_f32_e32 v144, 1.0, v144
	v_add_f32_e32 v135, 1.0, v135
	v_add_f32_e32 v134, 1.0, v134
	v_add_f32_e32 v133, 1.0, v133
	v_add_f32_e32 v132, 1.0, v132
	v_rcp_f32_e32 v162, v162
	v_rcp_f32_e32 v161, v161
	v_rcp_f32_e32 v160, v160
	v_rcp_f32_e32 v144, v144
	v_rcp_f32_e32 v135, v135
	v_rcp_f32_e32 v134, v134
	v_rcp_f32_e32 v133, v133
	v_rcp_f32_e32 v132, v132
	v_mul_f32_e32 v162, v99, v162
	v_mul_f32_e32 v161, v98, v161
	v_mul_f32_e32 v160, v97, v160
	v_mul_f32_e32 v144, v96, v144
	v_mul_f32_e32 v135, v103, v135
	v_mul_f32_e32 v134, v102, v134
	v_mul_f32_e32 v133, v101, v133
	v_mul_f32_e32 v132, v100, v132
.LBB0_311:
	v_cvt_pk_bf16_f32 v132, v132, v133
	v_cvt_pk_bf16_f32 v133, v134, v135
	v_cvt_pk_bf16_f32 v134, v144, v160
	v_cvt_pk_bf16_f32 v135, v161, v162
	global_store_dwordx4 v[130:131], v[132:135], off offset:256
	s_and_b64 vcc, exec, s[4:5]
	v_mov_b32_e32 v162, v91
	v_mov_b32_e32 v161, v90
	v_mov_b32_e32 v160, v89
	v_mov_b32_e32 v144, v88
	v_mov_b32_e32 v135, v95
	v_mov_b32_e32 v134, v94
	v_mov_b32_e32 v133, v93
	v_mov_b32_e32 v132, v92
	s_cbranch_vccnz .LBB0_313
	v_mul_f32_e32 v162, 0xbfb8aa3b, v91
	v_mul_f32_e32 v161, 0xbfb8aa3b, v90
	v_mul_f32_e32 v160, 0xbfb8aa3b, v89
	v_mul_f32_e32 v144, 0xbfb8aa3b, v88
	v_mul_f32_e32 v135, 0xbfb8aa3b, v95
	v_mul_f32_e32 v134, 0xbfb8aa3b, v94
	v_mul_f32_e32 v133, 0xbfb8aa3b, v93
	v_mul_f32_e32 v132, 0xbfb8aa3b, v92
	v_exp_f32_e32 v162, v162
	v_exp_f32_e32 v161, v161
	v_exp_f32_e32 v160, v160
	v_exp_f32_e32 v144, v144
	v_exp_f32_e32 v135, v135
	v_exp_f32_e32 v134, v134
	v_exp_f32_e32 v133, v133
	v_exp_f32_e32 v132, v132
	v_add_f32_e32 v162, 1.0, v162
	v_add_f32_e32 v161, 1.0, v161
	v_add_f32_e32 v160, 1.0, v160
	v_add_f32_e32 v144, 1.0, v144
	v_add_f32_e32 v135, 1.0, v135
	v_add_f32_e32 v134, 1.0, v134
	v_add_f32_e32 v133, 1.0, v133
	v_add_f32_e32 v132, 1.0, v132
	v_rcp_f32_e32 v162, v162
	v_rcp_f32_e32 v161, v161
	v_rcp_f32_e32 v160, v160
	v_rcp_f32_e32 v144, v144
	v_rcp_f32_e32 v135, v135
	v_rcp_f32_e32 v134, v134
	v_rcp_f32_e32 v133, v133
	v_rcp_f32_e32 v132, v132
	v_mul_f32_e32 v162, v91, v162
	v_mul_f32_e32 v161, v90, v161
	v_mul_f32_e32 v160, v89, v160
	v_mul_f32_e32 v144, v88, v144
	v_mul_f32_e32 v135, v95, v135
	v_mul_f32_e32 v134, v94, v134
	v_mul_f32_e32 v133, v93, v133
	v_mul_f32_e32 v132, v92, v132
.LBB0_313:
	v_or_b32_e32 v130, 32, v158
	v_ashrrev_i32_e32 v131, 31, v130
	v_lshlrev_b64 v[130:131], 13, v[130:131]
	v_lshl_add_u64 v[130:131], v[128:129], 0, v[130:131]
	v_cvt_pk_bf16_f32 v132, v132, v133
	v_cvt_pk_bf16_f32 v133, v134, v135
	v_cvt_pk_bf16_f32 v134, v144, v160
	v_cvt_pk_bf16_f32 v135, v161, v162
	global_store_dwordx4 v[130:131], v[132:135], off
	s_and_b64 vcc, exec, s[4:5]
	v_mov_b32_e32 v162, v83
	v_mov_b32_e32 v161, v82
	v_mov_b32_e32 v160, v81
	v_mov_b32_e32 v144, v80
	v_mov_b32_e32 v135, v87
	v_mov_b32_e32 v134, v86
	v_mov_b32_e32 v133, v85
	v_mov_b32_e32 v132, v84
	s_cbranch_vccnz .LBB0_315
	v_mul_f32_e32 v162, 0xbfb8aa3b, v83
	v_mul_f32_e32 v161, 0xbfb8aa3b, v82
	v_mul_f32_e32 v160, 0xbfb8aa3b, v81
	v_mul_f32_e32 v144, 0xbfb8aa3b, v80
	v_mul_f32_e32 v135, 0xbfb8aa3b, v87
	v_mul_f32_e32 v134, 0xbfb8aa3b, v86
	v_mul_f32_e32 v133, 0xbfb8aa3b, v85
	v_mul_f32_e32 v132, 0xbfb8aa3b, v84
	v_exp_f32_e32 v162, v162
	v_exp_f32_e32 v161, v161
	v_exp_f32_e32 v160, v160
	v_exp_f32_e32 v144, v144
	v_exp_f32_e32 v135, v135
	v_exp_f32_e32 v134, v134
	v_exp_f32_e32 v133, v133
	v_exp_f32_e32 v132, v132
	v_add_f32_e32 v162, 1.0, v162
	v_add_f32_e32 v161, 1.0, v161
	v_add_f32_e32 v160, 1.0, v160
	v_add_f32_e32 v144, 1.0, v144
	v_add_f32_e32 v135, 1.0, v135
	v_add_f32_e32 v134, 1.0, v134
	v_add_f32_e32 v133, 1.0, v133
	v_add_f32_e32 v132, 1.0, v132
	v_rcp_f32_e32 v162, v162
	v_rcp_f32_e32 v161, v161
	v_rcp_f32_e32 v160, v160
	v_rcp_f32_e32 v144, v144
	v_rcp_f32_e32 v135, v135
	v_rcp_f32_e32 v134, v134
	v_rcp_f32_e32 v133, v133
	v_rcp_f32_e32 v132, v132
	v_mul_f32_e32 v162, v83, v162
	v_mul_f32_e32 v161, v82, v161
	v_mul_f32_e32 v160, v81, v160
	v_mul_f32_e32 v144, v80, v144
	v_mul_f32_e32 v135, v87, v135
	v_mul_f32_e32 v134, v86, v134
	v_mul_f32_e32 v133, v85, v133
	v_mul_f32_e32 v132, v84, v132
; __device__ __forceinline__ unsigned cvt_pk_bf16(float lo, float hi) { unsigned r; asm volatile("v_cvt_pk_bf16_f32 %0, %1, %2" : "=v"(r) : "v"(lo), "v"(hi)); return r; }
; __device__ __forceinline__ float silu_f(float v) { return v / (1.0f + __expf(-v)); }
; __device__ __forceinline__ void st8(bf16_t* p, f32x4 v0, f32x4 v1) {
;     u32x4 w; w.x = cvt_pk_bf16(v0[0], v0[1]); w.y = cvt_pk_bf16(v0[2], v0[3]); w.z = cvt_pk_bf16(v1[0], v1[1]); w.w = cvt_pk_bf16(v1[2], v1[3]);
;     *(u32x4*)p = w;
; }
; __device__ __forceinline__ f32x4 silu4(f32x4 v) { f32x4 o; o[0] = silu_f(v[0]); o[1] = silu_f(v[1]); o[2] = silu_f(v[2]); o[3] = silu_f(v[3]); return o; }
;     __device__ __forceinline__ void operator()(const f32x4 (&acc)[2][2][4][2], const Unit& u, int wr, int wc, int fr, int fq) const {
;     ...
;             const bool isg = u.pn >= 32; bf16_t* base = (isg ? SG + (u.pn - 32) * 256 : V + (u.pn - 16) * 256) + cl;
; #pragma unroll
;             for (int ai = 0; ai < 2; ++ai)
; #pragma unroll
;                 for (int m = 0; m < 4; ++m) { bf16_t* rowp = base + (size_t)(row0 + ai * HALF + m * 16) * 4096;
; #pragma unroll
;                     for (int bj = 0; bj < 2; ++bj) { f32x4 v0 = acc[ai][bj][m][0], v1 = acc[ai][bj][m][1];
;                         if (isg) { v0 = silu4(v0); v1 = silu4(v1); }
;                         st8(rowp + bj * HALF, v0, v1); } }
.LBB0_315:
	v_cvt_pk_bf16_f32 v132, v132, v133
	v_cvt_pk_bf16_f32 v133, v134, v135
	v_cvt_pk_bf16_f32 v134, v144, v160
	v_cvt_pk_bf16_f32 v135, v161, v162
	global_store_dwordx4 v[130:131], v[132:135], off offset:256
	s_and_b64 vcc, exec, s[4:5]
	v_mov_b32_e32 v162, v75
	v_mov_b32_e32 v161, v74
	v_mov_b32_e32 v160, v73
	v_mov_b32_e32 v144, v72
	v_mov_b32_e32 v135, v79
	v_mov_b32_e32 v134, v78
	v_mov_b32_e32 v133, v77
	v_mov_b32_e32 v132, v76
	s_cbranch_vccnz .LBB0_317
	v_mul_f32_e32 v162, 0xbfb8aa3b, v75
	v_mul_f32_e32 v161, 0xbfb8aa3b, v74
	v_mul_f32_e32 v160, 0xbfb8aa3b, v73
	v_mul_f32_e32 v144, 0xbfb8aa3b, v72
	v_mul_f32_e32 v135, 0xbfb8aa3b, v79
	v_mul_f32_e32 v134, 0xbfb8aa3b, v78
	v_mul_f32_e32 v133, 0xbfb8aa3b, v77
	v_mul_f32_e32 v132, 0xbfb8aa3b, v76
	v_exp_f32_e32 v162, v162
	v_exp_f32_e32 v161, v161
	v_exp_f32_e32 v160, v160
	v_exp_f32_e32 v144, v144
	v_exp_f32_e32 v135, v135
	v_exp_f32_e32 v134, v134
	v_exp_f32_e32 v133, v133
	v_exp_f32_e32 v132, v132
	v_add_f32_e32 v162, 1.0, v162
	v_add_f32_e32 v161, 1.0, v161
	v_add_f32_e32 v160, 1.0, v160
	v_add_f32_e32 v144, 1.0, v144
	v_add_f32_e32 v135, 1.0, v135
	v_add_f32_e32 v134, 1.0, v134
	v_add_f32_e32 v133, 1.0, v133
	v_add_f32_e32 v132, 1.0, v132
	v_rcp_f32_e32 v162, v162
	v_rcp_f32_e32 v161, v161
	v_rcp_f32_e32 v160, v160
	v_rcp_f32_e32 v144, v144
	v_rcp_f32_e32 v135, v135
	v_rcp_f32_e32 v134, v134
	v_rcp_f32_e32 v133, v133
	v_rcp_f32_e32 v132, v132
	v_mul_f32_e32 v162, v75, v162
	v_mul_f32_e32 v161, v74, v161
	v_mul_f32_e32 v160, v73, v160
	v_mul_f32_e32 v144, v72, v144
	v_mul_f32_e32 v135, v79, v135
	v_mul_f32_e32 v134, v78, v134
	v_mul_f32_e32 v133, v77, v133
	v_mul_f32_e32 v132, v76, v132
.LBB0_317:
	v_or_b32_e32 v130, 48, v158
	v_ashrrev_i32_e32 v131, 31, v130
	v_lshlrev_b64 v[130:131], 13, v[130:131]
	v_lshl_add_u64 v[130:131], v[128:129], 0, v[130:131]
	v_cvt_pk_bf16_f32 v132, v132, v133
	v_cvt_pk_bf16_f32 v133, v134, v135
	v_cvt_pk_bf16_f32 v134, v144, v160
	v_cvt_pk_bf16_f32 v135, v161, v162
	global_store_dwordx4 v[130:131], v[132:135], off
	s_and_b64 vcc, exec, s[4:5]
	v_mov_b32_e32 v162, v67
	v_mov_b32_e32 v161, v66
	v_mov_b32_e32 v160, v65
	v_mov_b32_e32 v144, v64
	v_mov_b32_e32 v135, v71
	v_mov_b32_e32 v134, v70
	v_mov_b32_e32 v133, v69
	v_mov_b32_e32 v132, v68
	s_cbranch_vccnz .LBB0_319
	v_mul_f32_e32 v162, 0xbfb8aa3b, v67
	v_mul_f32_e32 v161, 0xbfb8aa3b, v66
	v_mul_f32_e32 v160, 0xbfb8aa3b, v65
	v_mul_f32_e32 v144, 0xbfb8aa3b, v64
	v_mul_f32_e32 v135, 0xbfb8aa3b, v71
	v_mul_f32_e32 v134, 0xbfb8aa3b, v70
	v_mul_f32_e32 v133, 0xbfb8aa3b, v69
	v_mul_f32_e32 v132, 0xbfb8aa3b, v68
	v_exp_f32_e32 v162, v162
	v_exp_f32_e32 v161, v161
	v_exp_f32_e32 v160, v160
	v_exp_f32_e32 v144, v144
	v_exp_f32_e32 v135, v135
	v_exp_f32_e32 v134, v134
	v_exp_f32_e32 v133, v133
	v_exp_f32_e32 v132, v132
	v_add_f32_e32 v162, 1.0, v162
	v_add_f32_e32 v161, 1.0, v161
	v_add_f32_e32 v160, 1.0, v160
	v_add_f32_e32 v144, 1.0, v144
	v_add_f32_e32 v135, 1.0, v135
	v_add_f32_e32 v134, 1.0, v134
	v_add_f32_e32 v133, 1.0, v133
	v_add_f32_e32 v132, 1.0, v132
	v_rcp_f32_e32 v162, v162
	v_rcp_f32_e32 v161, v161
	v_rcp_f32_e32 v160, v160
	v_rcp_f32_e32 v144, v144
	v_rcp_f32_e32 v135, v135
	v_rcp_f32_e32 v134, v134
	v_rcp_f32_e32 v133, v133
	v_rcp_f32_e32 v132, v132
	v_mul_f32_e32 v162, v67, v162
	v_mul_f32_e32 v161, v66, v161
	v_mul_f32_e32 v160, v65, v160
	v_mul_f32_e32 v144, v64, v144
	v_mul_f32_e32 v135, v71, v135
	v_mul_f32_e32 v134, v70, v134
	v_mul_f32_e32 v133, v69, v133
	v_mul_f32_e32 v132, v68, v132
.LBB0_319:
	v_cvt_pk_bf16_f32 v132, v132, v133
	v_cvt_pk_bf16_f32 v133, v134, v135
	v_cvt_pk_bf16_f32 v134, v144, v160
	v_cvt_pk_bf16_f32 v135, v161, v162
	global_store_dwordx4 v[130:131], v[132:135], off offset:256
	s_and_b64 vcc, exec, s[4:5]
	v_mov_b32_e32 v162, v59
	v_mov_b32_e32 v161, v58
	v_mov_b32_e32 v160, v57
	v_mov_b32_e32 v144, v56
	v_mov_b32_e32 v135, v63
	v_mov_b32_e32 v134, v62
	v_mov_b32_e32 v133, v61
	v_mov_b32_e32 v132, v60
	s_cbranch_vccnz .LBB0_321
	v_mul_f32_e32 v162, 0xbfb8aa3b, v59
	v_mul_f32_e32 v161, 0xbfb8aa3b, v58
	v_mul_f32_e32 v160, 0xbfb8aa3b, v57
	v_mul_f32_e32 v144, 0xbfb8aa3b, v56
	v_mul_f32_e32 v135, 0xbfb8aa3b, v63
	v_mul_f32_e32 v134, 0xbfb8aa3b, v62
	v_mul_f32_e32 v133, 0xbfb8aa3b, v61
	v_mul_f32_e32 v132, 0xbfb8aa3b, v60
	v_exp_f32_e32 v162, v162
	v_exp_f32_e32 v161, v161
	v_exp_f32_e32 v160, v160
	v_exp_f32_e32 v144, v144
	v_exp_f32_e32 v135, v135
	v_exp_f32_e32 v134, v134
	v_exp_f32_e32 v133, v133
	v_exp_f32_e32 v132, v132
	v_add_f32_e32 v162, 1.0, v162
	v_add_f32_e32 v161, 1.0, v161
	v_add_f32_e32 v160, 1.0, v160
	v_add_f32_e32 v144, 1.0, v144
	v_add_f32_e32 v135, 1.0, v135
	v_add_f32_e32 v134, 1.0, v134
	v_add_f32_e32 v133, 1.0, v133
	v_add_f32_e32 v132, 1.0, v132
	v_rcp_f32_e32 v162, v162
	v_rcp_f32_e32 v161, v161
	v_rcp_f32_e32 v160, v160
	v_rcp_f32_e32 v144, v144
	v_rcp_f32_e32 v135, v135
	v_rcp_f32_e32 v134, v134
	v_rcp_f32_e32 v133, v133
	v_rcp_f32_e32 v132, v132
	v_mul_f32_e32 v162, v59, v162
	v_mul_f32_e32 v161, v58, v161
	v_mul_f32_e32 v160, v57, v160
	v_mul_f32_e32 v144, v56, v144
	v_mul_f32_e32 v135, v63, v135
	v_mul_f32_e32 v134, v62, v134
	v_mul_f32_e32 v133, v61, v133
	v_mul_f32_e32 v132, v60, v132
; __device__ __forceinline__ unsigned cvt_pk_bf16(float lo, float hi) { unsigned r; asm volatile("v_cvt_pk_bf16_f32 %0, %1, %2" : "=v"(r) : "v"(lo), "v"(hi)); return r; }
; __device__ __forceinline__ float silu_f(float v) { return v / (1.0f + __expf(-v)); }
; __device__ __forceinline__ void st8(bf16_t* p, f32x4 v0, f32x4 v1) {
;     u32x4 w; w.x = cvt_pk_bf16(v0[0], v0[1]); w.y = cvt_pk_bf16(v0[2], v0[3]); w.z = cvt_pk_bf16(v1[0], v1[1]); w.w = cvt_pk_bf16(v1[2], v1[3]);
;     *(u32x4*)p = w;
; }
; __device__ __forceinline__ f32x4 silu4(f32x4 v) { f32x4 o; o[0] = silu_f(v[0]); o[1] = silu_f(v[1]); o[2] = silu_f(v[2]); o[3] = silu_f(v[3]); return o; }
;     __device__ __forceinline__ void operator()(const f32x4 (&acc)[2][2][4][2], const Unit& u, int wr, int wc, int fr, int fq) const {
;     ...
;             const bool isg = u.pn >= 32; bf16_t* base = (isg ? SG + (u.pn - 32) * 256 : V + (u.pn - 16) * 256) + cl;
; #pragma unroll
;             for (int ai = 0; ai < 2; ++ai)
; #pragma unroll
;                 for (int m = 0; m < 4; ++m) { bf16_t* rowp = base + (size_t)(row0 + ai * HALF + m * 16) * 4096;
; #pragma unroll
;                     for (int bj = 0; bj < 2; ++bj) { f32x4 v0 = acc[ai][bj][m][0], v1 = acc[ai][bj][m][1];
;                         if (isg) { v0 = silu4(v0); v1 = silu4(v1); }
;                         st8(rowp + bj * HALF, v0, v1); } }
.LBB0_321:
	v_lshlrev_b64 v[130:131], 13, v[158:159]
	v_lshl_add_u64 v[130:131], v[128:129], 0, v[130:131]
	v_cvt_pk_bf16_f32 v132, v132, v133
	v_cvt_pk_bf16_f32 v133, v134, v135
	v_cvt_pk_bf16_f32 v134, v144, v160
	v_add_co_u32_e32 v160, vcc, 0x100000, v130
	v_cvt_pk_bf16_f32 v135, v161, v162
	v_mov_b32_e32 v162, v51
	s_nop 0
	v_addc_co_u32_e32 v161, vcc, 0, v131, vcc
	global_store_dwordx4 v[160:161], v[132:135], off
	s_and_b64 vcc, exec, s[4:5]
	v_mov_b32_e32 v161, v50
	v_mov_b32_e32 v160, v49
	v_mov_b32_e32 v144, v48
	v_mov_b32_e32 v135, v55
	v_mov_b32_e32 v134, v54
	v_mov_b32_e32 v133, v53
	v_mov_b32_e32 v132, v52
	s_cbranch_vccnz .LBB0_323
	v_mul_f32_e32 v162, 0xbfb8aa3b, v51
	v_mul_f32_e32 v161, 0xbfb8aa3b, v50
	v_mul_f32_e32 v160, 0xbfb8aa3b, v49
	v_mul_f32_e32 v144, 0xbfb8aa3b, v48
	v_mul_f32_e32 v135, 0xbfb8aa3b, v55
	v_mul_f32_e32 v134, 0xbfb8aa3b, v54
	v_mul_f32_e32 v133, 0xbfb8aa3b, v53
	v_mul_f32_e32 v132, 0xbfb8aa3b, v52
	v_exp_f32_e32 v162, v162
	v_exp_f32_e32 v161, v161
	v_exp_f32_e32 v160, v160
	v_exp_f32_e32 v144, v144
	v_exp_f32_e32 v135, v135
	v_exp_f32_e32 v134, v134
	v_exp_f32_e32 v133, v133
	v_exp_f32_e32 v132, v132
	v_add_f32_e32 v162, 1.0, v162
	v_add_f32_e32 v161, 1.0, v161
	v_add_f32_e32 v160, 1.0, v160
	v_add_f32_e32 v144, 1.0, v144
	v_add_f32_e32 v135, 1.0, v135
	v_add_f32_e32 v134, 1.0, v134
	v_add_f32_e32 v133, 1.0, v133
	v_add_f32_e32 v132, 1.0, v132
	v_rcp_f32_e32 v162, v162
	v_rcp_f32_e32 v161, v161
	v_rcp_f32_e32 v160, v160
	v_rcp_f32_e32 v144, v144
	v_rcp_f32_e32 v135, v135
	v_rcp_f32_e32 v134, v134
	v_rcp_f32_e32 v133, v133
	v_rcp_f32_e32 v132, v132
	v_mul_f32_e32 v162, v51, v162
	v_mul_f32_e32 v161, v50, v161
	v_mul_f32_e32 v160, v49, v160
	v_mul_f32_e32 v144, v48, v144
	v_mul_f32_e32 v135, v55, v135
	v_mul_f32_e32 v134, v54, v134
	v_mul_f32_e32 v133, v53, v133
	v_mul_f32_e32 v132, v52, v132
.LBB0_323:
	v_lshl_add_u64 v[176:177], v[130:131], 0, s[16:17]
	v_cvt_pk_bf16_f32 v130, v132, v133
	v_cvt_pk_bf16_f32 v131, v134, v135
	v_cvt_pk_bf16_f32 v132, v144, v160
	v_cvt_pk_bf16_f32 v133, v161, v162
	global_store_dwordx4 v[176:177], v[130:133], off offset:256
	s_and_b64 vcc, exec, s[4:5]
	v_mov_b32_e32 v162, v43
	v_mov_b32_e32 v161, v42
	v_mov_b32_e32 v160, v41
	v_mov_b32_e32 v144, v40
	v_mov_b32_e32 v135, v47
	v_mov_b32_e32 v134, v46
	v_mov_b32_e32 v133, v45
	v_mov_b32_e32 v132, v44
	s_cbranch_vccnz .LBB0_325
	v_mul_f32_e32 v162, 0xbfb8aa3b, v43
	v_mul_f32_e32 v161, 0xbfb8aa3b, v42
	v_mul_f32_e32 v160, 0xbfb8aa3b, v41
	v_mul_f32_e32 v144, 0xbfb8aa3b, v40
	v_mul_f32_e32 v135, 0xbfb8aa3b, v47
	v_mul_f32_e32 v134, 0xbfb8aa3b, v46
	v_mul_f32_e32 v133, 0xbfb8aa3b, v45
	v_mul_f32_e32 v132, 0xbfb8aa3b, v44
	v_exp_f32_e32 v162, v162
	v_exp_f32_e32 v161, v161
	v_exp_f32_e32 v160, v160
	v_exp_f32_e32 v144, v144
	v_exp_f32_e32 v135, v135
	v_exp_f32_e32 v134, v134
	v_exp_f32_e32 v133, v133
	v_exp_f32_e32 v132, v132
	v_add_f32_e32 v162, 1.0, v162
	v_add_f32_e32 v161, 1.0, v161
	v_add_f32_e32 v160, 1.0, v160
	v_add_f32_e32 v144, 1.0, v144
	v_add_f32_e32 v135, 1.0, v135
	v_add_f32_e32 v134, 1.0, v134
	v_add_f32_e32 v133, 1.0, v133
	v_add_f32_e32 v132, 1.0, v132
	v_rcp_f32_e32 v162, v162
	v_rcp_f32_e32 v161, v161
	v_rcp_f32_e32 v160, v160
	v_rcp_f32_e32 v144, v144
	v_rcp_f32_e32 v135, v135
	v_rcp_f32_e32 v134, v134
	v_rcp_f32_e32 v133, v133
	v_rcp_f32_e32 v132, v132
	v_mul_f32_e32 v162, v43, v162
	v_mul_f32_e32 v161, v42, v161
	v_mul_f32_e32 v160, v41, v160
	v_mul_f32_e32 v144, v40, v144
	v_mul_f32_e32 v135, v47, v135
	v_mul_f32_e32 v134, v46, v134
	v_mul_f32_e32 v133, v45, v133
	v_mul_f32_e32 v132, v44, v132
.LBB0_325:
	v_lshlrev_b64 v[130:131], 13, v[158:159]
	v_lshl_add_u64 v[130:131], v[128:129], 0, v[130:131]
	v_cvt_pk_bf16_f32 v132, v132, v133
	v_cvt_pk_bf16_f32 v133, v134, v135
	v_cvt_pk_bf16_f32 v134, v144, v160
	v_add_co_u32_e32 v160, vcc, 0x120000, v130
	v_cvt_pk_bf16_f32 v135, v161, v162
	v_mov_b32_e32 v162, v35
	s_nop 0
	v_addc_co_u32_e32 v161, vcc, 0, v131, vcc
	global_store_dwordx4 v[160:161], v[132:135], off
	s_and_b64 vcc, exec, s[4:5]
	v_mov_b32_e32 v161, v34
	v_mov_b32_e32 v160, v33
	v_mov_b32_e32 v144, v32
	v_mov_b32_e32 v135, v39
	v_mov_b32_e32 v134, v38
	v_mov_b32_e32 v133, v37
	v_mov_b32_e32 v132, v36
	s_cbranch_vccnz .LBB0_327
	v_mul_f32_e32 v162, 0xbfb8aa3b, v35
	v_mul_f32_e32 v161, 0xbfb8aa3b, v34
	v_mul_f32_e32 v160, 0xbfb8aa3b, v33
	v_mul_f32_e32 v144, 0xbfb8aa3b, v32
	v_mul_f32_e32 v135, 0xbfb8aa3b, v39
	v_mul_f32_e32 v134, 0xbfb8aa3b, v38
	v_mul_f32_e32 v133, 0xbfb8aa3b, v37
	v_mul_f32_e32 v132, 0xbfb8aa3b, v36
	v_exp_f32_e32 v162, v162
	v_exp_f32_e32 v161, v161
	v_exp_f32_e32 v160, v160
	v_exp_f32_e32 v144, v144
	v_exp_f32_e32 v135, v135
	v_exp_f32_e32 v134, v134
	v_exp_f32_e32 v133, v133
	v_exp_f32_e32 v132, v132
	v_add_f32_e32 v162, 1.0, v162
	v_add_f32_e32 v161, 1.0, v161
	v_add_f32_e32 v160, 1.0, v160
	v_add_f32_e32 v144, 1.0, v144
	v_add_f32_e32 v135, 1.0, v135
	v_add_f32_e32 v134, 1.0, v134
	v_add_f32_e32 v133, 1.0, v133
	v_add_f32_e32 v132, 1.0, v132
	v_rcp_f32_e32 v162, v162
	v_rcp_f32_e32 v161, v161
	v_rcp_f32_e32 v160, v160
	v_rcp_f32_e32 v144, v144
	v_rcp_f32_e32 v135, v135
	v_rcp_f32_e32 v134, v134
	v_rcp_f32_e32 v133, v133
	v_rcp_f32_e32 v132, v132
	v_mul_f32_e32 v162, v35, v162
	v_mul_f32_e32 v161, v34, v161
	v_mul_f32_e32 v160, v33, v160
	v_mul_f32_e32 v144, v32, v144
	v_mul_f32_e32 v135, v39, v135
	v_mul_f32_e32 v134, v38, v134
	v_mul_f32_e32 v133, v37, v133
	v_mul_f32_e32 v132, v36, v132
; __device__ __forceinline__ unsigned cvt_pk_bf16(float lo, float hi) { unsigned r; asm volatile("v_cvt_pk_bf16_f32 %0, %1, %2" : "=v"(r) : "v"(lo), "v"(hi)); return r; }
; __device__ __forceinline__ float silu_f(float v) { return v / (1.0f + __expf(-v)); }
; __device__ __forceinline__ void st8(bf16_t* p, f32x4 v0, f32x4 v1) {
;     u32x4 w; w.x = cvt_pk_bf16(v0[0], v0[1]); w.y = cvt_pk_bf16(v0[2], v0[3]); w.z = cvt_pk_bf16(v1[0], v1[1]); w.w = cvt_pk_bf16(v1[2], v1[3]);
;     *(u32x4*)p = w;
; }
; __device__ __forceinline__ f32x4 silu4(f32x4 v) { f32x4 o; o[0] = silu_f(v[0]); o[1] = silu_f(v[1]); o[2] = silu_f(v[2]); o[3] = silu_f(v[3]); return o; }
;     __device__ __forceinline__ void operator()(const f32x4 (&acc)[2][2][4][2], const Unit& u, int wr, int wc, int fr, int fq) const {
;     ...
;             const bool isg = u.pn >= 32; bf16_t* base = (isg ? SG + (u.pn - 32) * 256 : V + (u.pn - 16) * 256) + cl;
; #pragma unroll
;             for (int ai = 0; ai < 2; ++ai)
; #pragma unroll
;                 for (int m = 0; m < 4; ++m) { bf16_t* rowp = base + (size_t)(row0 + ai * HALF + m * 16) * 4096;
; #pragma unroll
;                     for (int bj = 0; bj < 2; ++bj) { f32x4 v0 = acc[ai][bj][m][0], v1 = acc[ai][bj][m][1];
;                         if (isg) { v0 = silu4(v0); v1 = silu4(v1); }
;                         st8(rowp + bj * HALF, v0, v1); } }
.LBB0_327:
	v_lshl_add_u64 v[176:177], v[130:131], 0, s[18:19]
	v_cvt_pk_bf16_f32 v130, v132, v133
	v_cvt_pk_bf16_f32 v131, v134, v135
	v_cvt_pk_bf16_f32 v132, v144, v160
	v_cvt_pk_bf16_f32 v133, v161, v162
	global_store_dwordx4 v[176:177], v[130:133], off offset:256
	s_and_b64 vcc, exec, s[4:5]
	v_mov_b32_e32 v162, v27
	v_mov_b32_e32 v161, v26
	v_mov_b32_e32 v160, v25
	v_mov_b32_e32 v144, v24
	v_mov_b32_e32 v135, v31
	v_mov_b32_e32 v134, v30
	v_mov_b32_e32 v133, v29
	v_mov_b32_e32 v132, v28
	s_cbranch_vccnz .LBB0_329
	v_mul_f32_e32 v162, 0xbfb8aa3b, v27
	v_mul_f32_e32 v161, 0xbfb8aa3b, v26
	v_mul_f32_e32 v160, 0xbfb8aa3b, v25
	v_mul_f32_e32 v144, 0xbfb8aa3b, v24
	v_mul_f32_e32 v135, 0xbfb8aa3b, v31
	v_mul_f32_e32 v134, 0xbfb8aa3b, v30
	v_mul_f32_e32 v133, 0xbfb8aa3b, v29
	v_mul_f32_e32 v132, 0xbfb8aa3b, v28
	v_exp_f32_e32 v162, v162
	v_exp_f32_e32 v161, v161
	v_exp_f32_e32 v160, v160
	v_exp_f32_e32 v144, v144
	v_exp_f32_e32 v135, v135
	v_exp_f32_e32 v134, v134
	v_exp_f32_e32 v133, v133
	v_exp_f32_e32 v132, v132
	v_add_f32_e32 v162, 1.0, v162
	v_add_f32_e32 v161, 1.0, v161
	v_add_f32_e32 v160, 1.0, v160
	v_add_f32_e32 v144, 1.0, v144
	v_add_f32_e32 v135, 1.0, v135
	v_add_f32_e32 v134, 1.0, v134
	v_add_f32_e32 v133, 1.0, v133
	v_add_f32_e32 v132, 1.0, v132
	v_rcp_f32_e32 v162, v162
	v_rcp_f32_e32 v161, v161
	v_rcp_f32_e32 v160, v160
	v_rcp_f32_e32 v144, v144
	v_rcp_f32_e32 v135, v135
	v_rcp_f32_e32 v134, v134
	v_rcp_f32_e32 v133, v133
	v_rcp_f32_e32 v132, v132
	v_mul_f32_e32 v162, v27, v162
	v_mul_f32_e32 v161, v26, v161
	v_mul_f32_e32 v160, v25, v160
	v_mul_f32_e32 v144, v24, v144
	v_mul_f32_e32 v135, v31, v135
	v_mul_f32_e32 v134, v30, v134
	v_mul_f32_e32 v133, v29, v133
	v_mul_f32_e32 v132, v28, v132
.LBB0_329:
	v_lshlrev_b64 v[130:131], 13, v[158:159]
	v_lshl_add_u64 v[130:131], v[128:129], 0, v[130:131]
	v_cvt_pk_bf16_f32 v132, v132, v133
	v_cvt_pk_bf16_f32 v133, v134, v135
	v_cvt_pk_bf16_f32 v134, v144, v160
	v_add_co_u32_e32 v160, vcc, 0x140000, v130
	v_cvt_pk_bf16_f32 v135, v161, v162
	v_mov_b32_e32 v162, v19
	s_nop 0
	v_addc_co_u32_e32 v161, vcc, 0, v131, vcc
	global_store_dwordx4 v[160:161], v[132:135], off
	s_and_b64 vcc, exec, s[4:5]
	v_mov_b32_e32 v161, v18
	v_mov_b32_e32 v160, v17
	v_mov_b32_e32 v144, v16
	v_mov_b32_e32 v135, v23
	v_mov_b32_e32 v134, v22
	v_mov_b32_e32 v133, v21
	v_mov_b32_e32 v132, v20
	s_cbranch_vccnz .LBB0_331
	v_mul_f32_e32 v162, 0xbfb8aa3b, v19
	v_mul_f32_e32 v161, 0xbfb8aa3b, v18
	v_mul_f32_e32 v160, 0xbfb8aa3b, v17
	v_mul_f32_e32 v144, 0xbfb8aa3b, v16
	v_mul_f32_e32 v135, 0xbfb8aa3b, v23
	v_mul_f32_e32 v134, 0xbfb8aa3b, v22
	v_mul_f32_e32 v133, 0xbfb8aa3b, v21
	v_mul_f32_e32 v132, 0xbfb8aa3b, v20
	v_exp_f32_e32 v162, v162
	v_exp_f32_e32 v161, v161
	v_exp_f32_e32 v160, v160
	v_exp_f32_e32 v144, v144
	v_exp_f32_e32 v135, v135
	v_exp_f32_e32 v134, v134
	v_exp_f32_e32 v133, v133
	v_exp_f32_e32 v132, v132
	v_add_f32_e32 v162, 1.0, v162
	v_add_f32_e32 v161, 1.0, v161
	v_add_f32_e32 v160, 1.0, v160
	v_add_f32_e32 v144, 1.0, v144
	v_add_f32_e32 v135, 1.0, v135
	v_add_f32_e32 v134, 1.0, v134
	v_add_f32_e32 v133, 1.0, v133
	v_add_f32_e32 v132, 1.0, v132
	v_rcp_f32_e32 v162, v162
	v_rcp_f32_e32 v161, v161
	v_rcp_f32_e32 v160, v160
	v_rcp_f32_e32 v144, v144
	v_rcp_f32_e32 v135, v135
	v_rcp_f32_e32 v134, v134
	v_rcp_f32_e32 v133, v133
	v_rcp_f32_e32 v132, v132
	v_mul_f32_e32 v162, v19, v162
	v_mul_f32_e32 v161, v18, v161
	v_mul_f32_e32 v160, v17, v160
	v_mul_f32_e32 v144, v16, v144
	v_mul_f32_e32 v135, v23, v135
	v_mul_f32_e32 v134, v22, v134
	v_mul_f32_e32 v133, v21, v133
	v_mul_f32_e32 v132, v20, v132
; __device__ __forceinline__ unsigned cvt_pk_bf16(float lo, float hi) { unsigned r; asm volatile("v_cvt_pk_bf16_f32 %0, %1, %2" : "=v"(r) : "v"(lo), "v"(hi)); return r; }
; __device__ __forceinline__ float silu_f(float v) { return v / (1.0f + __expf(-v)); }
; __device__ __forceinline__ void st8(bf16_t* p, f32x4 v0, f32x4 v1) {
;     u32x4 w; w.x = cvt_pk_bf16(v0[0], v0[1]); w.y = cvt_pk_bf16(v0[2], v0[3]); w.z = cvt_pk_bf16(v1[0], v1[1]); w.w = cvt_pk_bf16(v1[2], v1[3]);
;     *(u32x4*)p = w;
; }
; __device__ __forceinline__ f32x4 silu4(f32x4 v) { f32x4 o; o[0] = silu_f(v[0]); o[1] = silu_f(v[1]); o[2] = silu_f(v[2]); o[3] = silu_f(v[3]); return o; }
;     __device__ __forceinline__ void operator()(const f32x4 (&acc)[2][2][4][2], const Unit& u, int wr, int wc, int fr, int fq) const {
;     ...
;             const bool isg = u.pn >= 32; bf16_t* base = (isg ? SG + (u.pn - 32) * 256 : V + (u.pn - 16) * 256) + cl;
; #pragma unroll
;             for (int ai = 0; ai < 2; ++ai)
; #pragma unroll
;                 for (int m = 0; m < 4; ++m) { bf16_t* rowp = base + (size_t)(row0 + ai * HALF + m * 16) * 4096;
; #pragma unroll
;                     for (int bj = 0; bj < 2; ++bj) { f32x4 v0 = acc[ai][bj][m][0], v1 = acc[ai][bj][m][1];
;                         if (isg) { v0 = silu4(v0); v1 = silu4(v1); }
;                         st8(rowp + bj * HALF, v0, v1); } }
.LBB0_331:
	v_lshl_add_u64 v[176:177], v[130:131], 0, s[20:21]
	v_cvt_pk_bf16_f32 v130, v132, v133
	v_cvt_pk_bf16_f32 v131, v134, v135
	v_cvt_pk_bf16_f32 v132, v144, v160
	v_cvt_pk_bf16_f32 v133, v161, v162
	global_store_dwordx4 v[176:177], v[130:133], off offset:256
	s_and_b64 vcc, exec, s[4:5]
	v_mov_b32_e32 v160, v11
	v_mov_b32_e32 v144, v10
	v_mov_b32_e32 v135, v9
	v_mov_b32_e32 v134, v8
	v_mov_b32_e32 v133, v15
	v_mov_b32_e32 v132, v14
	v_mov_b32_e32 v131, v13
	v_mov_b32_e32 v130, v12
	s_cbranch_vccnz .LBB0_333
	v_mul_f32_e32 v160, 0xbfb8aa3b, v11
	v_mul_f32_e32 v144, 0xbfb8aa3b, v10
	v_mul_f32_e32 v135, 0xbfb8aa3b, v9
	v_mul_f32_e32 v134, 0xbfb8aa3b, v8
	v_mul_f32_e32 v133, 0xbfb8aa3b, v15
	v_mul_f32_e32 v132, 0xbfb8aa3b, v14
	v_mul_f32_e32 v131, 0xbfb8aa3b, v13
	v_mul_f32_e32 v130, 0xbfb8aa3b, v12
	v_exp_f32_e32 v160, v160
	v_exp_f32_e32 v144, v144
	v_exp_f32_e32 v135, v135
	v_exp_f32_e32 v134, v134
	v_exp_f32_e32 v133, v133
	v_exp_f32_e32 v132, v132
	v_exp_f32_e32 v131, v131
	v_exp_f32_e32 v130, v130
	v_add_f32_e32 v160, 1.0, v160
	v_add_f32_e32 v144, 1.0, v144
	v_add_f32_e32 v135, 1.0, v135
	v_add_f32_e32 v134, 1.0, v134
	v_add_f32_e32 v133, 1.0, v133
	v_add_f32_e32 v132, 1.0, v132
	v_add_f32_e32 v131, 1.0, v131
	v_add_f32_e32 v130, 1.0, v130
	v_rcp_f32_e32 v160, v160
	v_rcp_f32_e32 v144, v144
	v_rcp_f32_e32 v135, v135
	v_rcp_f32_e32 v134, v134
	v_rcp_f32_e32 v133, v133
	v_rcp_f32_e32 v132, v132
	v_rcp_f32_e32 v131, v131
	v_rcp_f32_e32 v130, v130
	v_mul_f32_e32 v160, v11, v160
	v_mul_f32_e32 v144, v10, v144
	v_mul_f32_e32 v135, v9, v135
	v_mul_f32_e32 v134, v8, v134
	v_mul_f32_e32 v133, v15, v133
	v_mul_f32_e32 v132, v14, v132
	v_mul_f32_e32 v131, v13, v131
	v_mul_f32_e32 v130, v12, v130
.LBB0_333:
	v_lshlrev_b64 v[162:163], 13, v[158:159]
	v_lshl_add_u64 v[128:129], v[128:129], 0, v[162:163]
	v_cvt_pk_bf16_f32 v130, v130, v131
	v_cvt_pk_bf16_f32 v131, v132, v133
	v_cvt_pk_bf16_f32 v132, v134, v135
	v_add_co_u32_e32 v134, vcc, 0x160000, v128
	v_cvt_pk_bf16_f32 v133, v144, v160
	v_mov_b32_e32 v159, v3
	s_nop 0
	v_addc_co_u32_e32 v135, vcc, 0, v129, vcc
	global_store_dwordx4 v[134:135], v[130:133], off
	s_and_b64 vcc, exec, s[4:5]
	v_mov_b32_e32 v144, v2
	v_mov_b32_e32 v135, v1
	v_mov_b32_e32 v134, v0
	v_mov_b32_e32 v133, v7
	v_mov_b32_e32 v132, v6
	v_mov_b32_e32 v131, v5
	v_mov_b32_e32 v130, v4
	s_cbranch_vccnz .LBB0_335
	v_mul_f32_e32 v159, 0xbfb8aa3b, v3
	v_mul_f32_e32 v144, 0xbfb8aa3b, v2
	v_mul_f32_e32 v135, 0xbfb8aa3b, v1
	v_mul_f32_e32 v134, 0xbfb8aa3b, v0
	v_mul_f32_e32 v133, 0xbfb8aa3b, v7
	v_mul_f32_e32 v132, 0xbfb8aa3b, v6
	v_mul_f32_e32 v131, 0xbfb8aa3b, v5
	v_mul_f32_e32 v130, 0xbfb8aa3b, v4
	v_exp_f32_e32 v159, v159
	v_exp_f32_e32 v144, v144
	v_exp_f32_e32 v135, v135
	v_exp_f32_e32 v134, v134
	v_exp_f32_e32 v133, v133
	v_exp_f32_e32 v132, v132
	v_exp_f32_e32 v131, v131
	v_exp_f32_e32 v130, v130
	v_add_f32_e32 v159, 1.0, v159
	v_add_f32_e32 v144, 1.0, v144
	v_add_f32_e32 v135, 1.0, v135
	v_add_f32_e32 v134, 1.0, v134
	v_add_f32_e32 v133, 1.0, v133
	v_add_f32_e32 v132, 1.0, v132
	v_add_f32_e32 v131, 1.0, v131
	v_add_f32_e32 v130, 1.0, v130
	v_rcp_f32_e32 v159, v159
	v_rcp_f32_e32 v144, v144
	v_rcp_f32_e32 v135, v135
	v_rcp_f32_e32 v134, v134
	v_rcp_f32_e32 v133, v133
	v_rcp_f32_e32 v132, v132
	v_rcp_f32_e32 v131, v131
	v_rcp_f32_e32 v130, v130
	v_mul_f32_e32 v159, v3, v159
	v_mul_f32_e32 v144, v2, v144
	v_mul_f32_e32 v135, v1, v135
	v_mul_f32_e32 v134, v0, v134
	v_mul_f32_e32 v133, v7, v133
	v_mul_f32_e32 v132, v6, v132
	v_mul_f32_e32 v131, v5, v131
	v_mul_f32_e32 v130, v4, v130

; __device__ __forceinline__ void sincos_rr(float ang, float& s, float& c) {
;     const float k = rintf(ang * 0.15915494309189535f);
;     float r = fmaf(-k, 6.2831854820251465f, ang);
;     r = fmaf(-k, -1.7484555e-7f, r);
;     const float rev = r * 0.15915494309189535f;
;     s = __builtin_amdgcn_sinf(rev); c = __builtin_amdgcn_cosf(rev);
; }
;     __device__ __forceinline__ void operator()(const f32x4 (&acc)[2][2][4][2], const Unit& u, int wr, int wc, int fr, int fq) const {
;     ...
;         } else if (wc < 2) {
;             const f32x4 invf = *(const f32x4*)(INVF64 + 16 * wc + 4 * fq);
; #pragma unroll
;             for (int ai = 0; ai < 2; ++ai)
; #pragma unroll
;                 for (int m = 0; m < 4; ++m) { const int row = row0 + ai * HALF + m * 16; const float p = (float)pos[row]; f32x4 o0, o1;
; #pragma unroll
;                     for (int e = 0; e < 4; ++e) { float s, c; sincos_rr(p * invf[e], s, c);
;                         const float x1 = acc[ai][0][m][0][e], x2 = acc[ai][0][m][1][e];
;                         o0[e] = x1 * c - x2 * s; o1[e] = x2 * c + x1 * s; }
;                     st8(KR + (size_t)row * 64 + cl, o0, o1); }
.LBB0_772:
	s_cmp_gt_u32 s46, 11
	s_cbranch_scc0 .LBB0_776
	s_andn2_b64 vcc, exec, s[14:15]
	s_cbranch_vccnz .LBB0_775
	v_ashrrev_i32_e32 v157, 31, v156
	v_lshl_add_u64 v[158:159], v[156:157], 2, s[44:45]
	global_load_dword v140, v[158:159], off
	global_load_dwordx4 v[128:131], v[144:145], off
	v_lshlrev_b64 v[160:161], 7, v[156:157]
	v_mov_b32_e32 v162, v124
	v_mov_b32_e32 v163, v120
	v_mov_b32_e32 v170, v125
	v_mov_b32_e32 v171, v121
	v_mov_b32_e32 v172, v126
	v_mov_b32_e32 v173, v122
	v_mov_b32_e32 v174, v127
	v_mov_b32_e32 v175, v123
	v_lshl_add_u64 v[160:161], v[146:147], 0, v[160:161]
	s_movk_i32 s31, 0x5000
	s_waitcnt vmcnt(0)
	v_cvt_f32_i32_e32 v140, v140
	v_mul_f32_e32 v177, v130, v140
	v_mul_f32_e32 v157, v128, v140
	v_mul_f32_e32 v176, v129, v140
	v_mul_f32_e32 v140, v131, v140
	v_mul_f32_e32 v180, 0.15915494, v177
	v_mul_f32_e32 v178, 0.15915494, v157
	v_mul_f32_e32 v179, 0.15915494, v176
	v_mul_f32_e32 v181, 0.15915494, v140
	v_rndne_f32_e32 v180, v180
	v_rndne_f32_e32 v178, v178
	v_rndne_f32_e32 v179, v179
	v_rndne_f32_e32 v181, v181
	v_fmac_f32_e32 v177, 0xc0c90fdb, v180
	v_fmac_f32_e32 v157, 0xc0c90fdb, v178
	v_fmac_f32_e32 v176, 0xc0c90fdb, v179
	v_fmac_f32_e32 v140, 0xc0c90fdb, v181
	v_fmac_f32_e32 v177, 0x343bbd2e, v180
	v_fmac_f32_e32 v157, 0x343bbd2e, v178
	v_fmac_f32_e32 v176, 0x343bbd2e, v179
	v_fmac_f32_e32 v140, 0x343bbd2e, v181
	v_mul_f32_e32 v180, 0.15915494, v177
	v_mul_f32_e32 v157, 0.15915494, v157
	v_mul_f32_e32 v178, 0.15915494, v176
	v_mul_f32_e32 v140, 0.15915494, v140
	v_sin_f32_e32 v181, v180
	v_cos_f32_e32 v180, v180
	v_sin_f32_e32 v177, v157
	v_cos_f32_e32 v176, v157
	v_sin_f32_e32 v179, v178
	v_cos_f32_e32 v178, v178
	v_sin_f32_e32 v183, v140
	v_cos_f32_e32 v182, v140
	v_mov_b32_e32 v190, v181
	v_mov_b32_e32 v191, v180
	v_pk_mul_f32 v[184:185], v[162:163], v[176:177]
	v_mov_b32_e32 v186, v177
	v_mov_b32_e32 v187, v176
	v_pk_mul_f32 v[176:177], v[170:171], v[178:179]
	v_mov_b32_e32 v188, v179
	v_mov_b32_e32 v189, v178
	v_pk_mul_f32 v[178:179], v[172:173], v[180:181]
	v_mov_b32_e32 v192, v183
	v_mov_b32_e32 v193, v182
	v_pk_mul_f32 v[172:173], v[172:173], v[190:191]
	v_pk_mul_f32 v[180:181], v[174:175], v[182:183]
	v_pk_mul_f32 v[162:163], v[162:163], v[186:187]
	v_pk_mul_f32 v[170:171], v[170:171], v[188:189]
	v_pk_mul_f32 v[174:175], v[174:175], v[192:193]
	v_add_f32_e32 v173, v172, v173
	v_sub_f32_e32 v140, v184, v185
	v_sub_f32_e32 v157, v176, v177
	v_sub_f32_e32 v176, v178, v179
	v_sub_f32_e32 v177, v180, v181
	v_add_f32_e32 v162, v162, v163
	v_add_f32_e32 v163, v170, v171
	v_add_f32_e32 v174, v174, v175
	v_cvt_pk_bf16_f32 v170, v140, v157
	v_cvt_pk_bf16_f32 v171, v176, v177
	v_cvt_pk_bf16_f32 v172, v162, v163
	v_cvt_pk_bf16_f32 v173, v173, v174
	global_store_dwordx4 v[160:161], v[170:173], off
	global_load_dword v140, v[158:159], off offset:64
	v_or_b32_e32 v162, 16, v156
	v_mov_b32_e32 v170, v108
	v_mov_b32_e32 v171, v104
	v_mov_b32_e32 v172, v109
	v_mov_b32_e32 v173, v105
	v_mov_b32_e32 v174, v110
	v_mov_b32_e32 v175, v106
	v_ashrrev_i32_e32 v163, 31, v162
	v_mov_b32_e32 v176, v111
	v_mov_b32_e32 v177, v107
	v_lshlrev_b64 v[162:163], 7, v[162:163]
	v_lshl_add_u64 v[162:163], v[146:147], 0, v[162:163]
	s_waitcnt vmcnt(0)
	v_cvt_f32_i32_e32 v140, v140
	v_mul_f32_e32 v178, v129, v140
	v_mul_f32_e32 v179, v130, v140
	v_mul_f32_e32 v157, v128, v140
	v_mul_f32_e32 v140, v131, v140
	v_mul_f32_e32 v181, 0.15915494, v178
	v_mul_f32_e32 v182, 0.15915494, v179
	v_mul_f32_e32 v180, 0.15915494, v157
	v_mul_f32_e32 v183, 0.15915494, v140
	v_rndne_f32_e32 v181, v181
	v_rndne_f32_e32 v182, v182
	v_rndne_f32_e32 v180, v180
	v_rndne_f32_e32 v183, v183
	v_fmac_f32_e32 v178, 0xc0c90fdb, v181
	v_fmac_f32_e32 v179, 0xc0c90fdb, v182
	v_fmac_f32_e32 v157, 0xc0c90fdb, v180
	v_fmac_f32_e32 v140, 0xc0c90fdb, v183
	v_fmac_f32_e32 v178, 0x343bbd2e, v181
	v_fmac_f32_e32 v179, 0x343bbd2e, v182
	v_fmac_f32_e32 v157, 0x343bbd2e, v180
	v_fmac_f32_e32 v140, 0x343bbd2e, v183
	v_mul_f32_e32 v180, 0.15915494, v178
	v_mul_f32_e32 v182, 0.15915494, v179
	v_mul_f32_e32 v157, 0.15915494, v157
	v_mul_f32_e32 v140, 0.15915494, v140
	v_sin_f32_e32 v181, v180
	v_cos_f32_e32 v180, v180
	v_sin_f32_e32 v183, v182
	v_cos_f32_e32 v182, v182
	v_sin_f32_e32 v179, v157
	v_cos_f32_e32 v178, v157
	v_sin_f32_e32 v185, v140
	v_cos_f32_e32 v184, v140
	v_mov_b32_e32 v190, v181
	v_mov_b32_e32 v191, v180
	v_mov_b32_e32 v192, v183
	v_mov_b32_e32 v193, v182
	v_pk_mul_f32 v[186:187], v[170:171], v[178:179]
	v_mov_b32_e32 v188, v179
	v_mov_b32_e32 v189, v178
	v_pk_mul_f32 v[178:179], v[172:173], v[180:181]
	v_pk_mul_f32 v[180:181], v[174:175], v[182:183]
	v_mov_b32_e32 v194, v185
	v_mov_b32_e32 v195, v184
	v_pk_mul_f32 v[172:173], v[172:173], v[190:191]
	v_pk_mul_f32 v[174:175], v[174:175], v[192:193]
	v_pk_mul_f32 v[182:183], v[176:177], v[184:185]
	v_pk_mul_f32 v[170:171], v[170:171], v[188:189]
	v_pk_mul_f32 v[176:177], v[176:177], v[194:195]
	v_add_f32_e32 v172, v172, v173
	v_add_f32_e32 v173, v174, v175
	v_sub_f32_e32 v140, v186, v187
	v_sub_f32_e32 v157, v178, v179
	v_sub_f32_e32 v178, v180, v181
	v_sub_f32_e32 v179, v182, v183
	v_add_f32_e32 v180, v170, v171
	v_add_f32_e32 v174, v176, v177
	v_cvt_pk_bf16_f32 v170, v140, v157
	v_cvt_pk_bf16_f32 v171, v178, v179
	v_cvt_pk_bf16_f32 v172, v180, v172
	v_cvt_pk_bf16_f32 v173, v173, v174
	global_store_dwordx4 v[162:163], v[170:173], off
	global_load_dword v140, v[158:159], off offset:128
	v_or_b32_e32 v162, 32, v156
	v_mov_b32_e32 v170, v92
	v_mov_b32_e32 v171, v88
	v_mov_b32_e32 v172, v93
	v_mov_b32_e32 v173, v89
	v_mov_b32_e32 v174, v94
	v_mov_b32_e32 v175, v90
	v_ashrrev_i32_e32 v163, 31, v162
	v_mov_b32_e32 v176, v95
	v_mov_b32_e32 v177, v91
	v_lshlrev_b64 v[162:163], 7, v[162:163]
	v_lshl_add_u64 v[162:163], v[146:147], 0, v[162:163]
	s_waitcnt vmcnt(0)
; __device__ __forceinline__ void sincos_rr(float ang, float& s, float& c) {
;     const float k = rintf(ang * 0.15915494309189535f);
;     float r = fmaf(-k, 6.2831854820251465f, ang);
;     r = fmaf(-k, -1.7484555e-7f, r);
;     const float rev = r * 0.15915494309189535f;
;     s = __builtin_amdgcn_sinf(rev); c = __builtin_amdgcn_cosf(rev);
; }
;     __device__ __forceinline__ void operator()(const f32x4 (&acc)[2][2][4][2], const Unit& u, int wr, int wc, int fr, int fq) const {
;     ...
;         } else if (wc < 2) {
;             const f32x4 invf = *(const f32x4*)(INVF64 + 16 * wc + 4 * fq);
; #pragma unroll
;             for (int ai = 0; ai < 2; ++ai)
; #pragma unroll
;                 for (int m = 0; m < 4; ++m) { const int row = row0 + ai * HALF + m * 16; const float p = (float)pos[row]; f32x4 o0, o1;
; #pragma unroll
;                     for (int e = 0; e < 4; ++e) { float s, c; sincos_rr(p * invf[e], s, c);
;                         const float x1 = acc[ai][0][m][0][e], x2 = acc[ai][0][m][1][e];
;                         o0[e] = x1 * c - x2 * s; o1[e] = x2 * c + x1 * s; }
;                     st8(KR + (size_t)row * 64 + cl, o0, o1); }
	v_cvt_f32_i32_e32 v140, v140
	v_mul_f32_e32 v178, v129, v140
	v_mul_f32_e32 v179, v130, v140
	v_mul_f32_e32 v157, v128, v140
	v_mul_f32_e32 v140, v131, v140
	v_mul_f32_e32 v181, 0.15915494, v178
	v_mul_f32_e32 v182, 0.15915494, v179
	v_mul_f32_e32 v180, 0.15915494, v157
	v_mul_f32_e32 v183, 0.15915494, v140
	v_rndne_f32_e32 v181, v181
	v_rndne_f32_e32 v182, v182
	v_rndne_f32_e32 v180, v180
	v_rndne_f32_e32 v183, v183
	v_fmac_f32_e32 v178, 0xc0c90fdb, v181
	v_fmac_f32_e32 v179, 0xc0c90fdb, v182
	v_fmac_f32_e32 v157, 0xc0c90fdb, v180
	v_fmac_f32_e32 v140, 0xc0c90fdb, v183
	v_fmac_f32_e32 v178, 0x343bbd2e, v181
	v_fmac_f32_e32 v179, 0x343bbd2e, v182
	v_fmac_f32_e32 v157, 0x343bbd2e, v180
	v_fmac_f32_e32 v140, 0x343bbd2e, v183
	v_mul_f32_e32 v180, 0.15915494, v178
	v_mul_f32_e32 v182, 0.15915494, v179
	v_mul_f32_e32 v157, 0.15915494, v157
	v_mul_f32_e32 v140, 0.15915494, v140
	v_sin_f32_e32 v181, v180
	v_cos_f32_e32 v180, v180
	v_sin_f32_e32 v183, v182
	v_cos_f32_e32 v182, v182
	v_sin_f32_e32 v179, v157
	v_cos_f32_e32 v178, v157
	v_sin_f32_e32 v185, v140
	v_cos_f32_e32 v184, v140
	v_mov_b32_e32 v190, v181
	v_mov_b32_e32 v191, v180
	v_mov_b32_e32 v192, v183
	v_mov_b32_e32 v193, v182
	v_pk_mul_f32 v[186:187], v[170:171], v[178:179]
	v_mov_b32_e32 v188, v179
	v_mov_b32_e32 v189, v178
	v_pk_mul_f32 v[178:179], v[172:173], v[180:181]
	v_pk_mul_f32 v[180:181], v[174:175], v[182:183]
	v_mov_b32_e32 v194, v185
	v_mov_b32_e32 v195, v184
	v_pk_mul_f32 v[172:173], v[172:173], v[190:191]
	v_pk_mul_f32 v[174:175], v[174:175], v[192:193]
	v_pk_mul_f32 v[182:183], v[176:177], v[184:185]
	v_pk_mul_f32 v[170:171], v[170:171], v[188:189]
	v_pk_mul_f32 v[176:177], v[176:177], v[194:195]
	v_add_f32_e32 v172, v172, v173
	v_add_f32_e32 v173, v174, v175
	v_sub_f32_e32 v140, v186, v187
	v_sub_f32_e32 v157, v178, v179
	v_sub_f32_e32 v178, v180, v181
	v_sub_f32_e32 v179, v182, v183
	v_add_f32_e32 v180, v170, v171
	v_add_f32_e32 v174, v176, v177
	v_cvt_pk_bf16_f32 v170, v140, v157
	v_cvt_pk_bf16_f32 v171, v178, v179
	v_cvt_pk_bf16_f32 v172, v180, v172
	v_cvt_pk_bf16_f32 v173, v173, v174
	global_store_dwordx4 v[162:163], v[170:173], off
	global_load_dword v140, v[158:159], off offset:192
	v_or_b32_e32 v162, 48, v156
	v_mov_b32_e32 v170, v76
	v_mov_b32_e32 v171, v72
	v_mov_b32_e32 v172, v77
	v_mov_b32_e32 v173, v73
	v_mov_b32_e32 v174, v78
	v_mov_b32_e32 v175, v74
	v_ashrrev_i32_e32 v163, 31, v162
	v_mov_b32_e32 v176, v79
	v_mov_b32_e32 v177, v75
	v_lshlrev_b64 v[162:163], 7, v[162:163]
	v_lshl_add_u64 v[162:163], v[146:147], 0, v[162:163]
	s_waitcnt vmcnt(0)
	v_cvt_f32_i32_e32 v140, v140
	v_mul_f32_e32 v178, v129, v140
	v_mul_f32_e32 v179, v130, v140
	v_mul_f32_e32 v157, v128, v140
	v_mul_f32_e32 v140, v131, v140
	v_mul_f32_e32 v181, 0.15915494, v178
	v_mul_f32_e32 v182, 0.15915494, v179
	v_mul_f32_e32 v180, 0.15915494, v157
	v_mul_f32_e32 v183, 0.15915494, v140
	v_rndne_f32_e32 v181, v181
	v_rndne_f32_e32 v182, v182
	v_rndne_f32_e32 v180, v180
	v_rndne_f32_e32 v183, v183
	v_fmac_f32_e32 v178, 0xc0c90fdb, v181
	v_fmac_f32_e32 v179, 0xc0c90fdb, v182
	v_fmac_f32_e32 v157, 0xc0c90fdb, v180
	v_fmac_f32_e32 v140, 0xc0c90fdb, v183
	v_fmac_f32_e32 v178, 0x343bbd2e, v181
	v_fmac_f32_e32 v179, 0x343bbd2e, v182
	v_fmac_f32_e32 v157, 0x343bbd2e, v180
	v_fmac_f32_e32 v140, 0x343bbd2e, v183
	v_mul_f32_e32 v180, 0.15915494, v178
	v_mul_f32_e32 v182, 0.15915494, v179
	v_mul_f32_e32 v157, 0.15915494, v157
	v_mul_f32_e32 v140, 0.15915494, v140
	v_sin_f32_e32 v181, v180
	v_cos_f32_e32 v180, v180
	v_sin_f32_e32 v183, v182
	v_cos_f32_e32 v182, v182
	v_sin_f32_e32 v179, v157
	v_cos_f32_e32 v178, v157
	v_sin_f32_e32 v185, v140
	v_cos_f32_e32 v184, v140
	v_mov_b32_e32 v190, v181
	v_mov_b32_e32 v191, v180
	v_mov_b32_e32 v192, v183
	v_mov_b32_e32 v193, v182
	v_pk_mul_f32 v[186:187], v[170:171], v[178:179]
	v_mov_b32_e32 v188, v179
	v_mov_b32_e32 v189, v178
	v_pk_mul_f32 v[178:179], v[172:173], v[180:181]
	v_pk_mul_f32 v[180:181], v[174:175], v[182:183]
	v_mov_b32_e32 v194, v185
	v_mov_b32_e32 v195, v184
	v_pk_mul_f32 v[172:173], v[172:173], v[190:191]
	v_pk_mul_f32 v[174:175], v[174:175], v[192:193]
	v_pk_mul_f32 v[182:183], v[176:177], v[184:185]
	v_pk_mul_f32 v[170:171], v[170:171], v[188:189]
	v_pk_mul_f32 v[176:177], v[176:177], v[194:195]
	v_add_f32_e32 v172, v172, v173
	v_add_f32_e32 v173, v174, v175
	v_sub_f32_e32 v140, v186, v187
	v_sub_f32_e32 v157, v178, v179
	v_sub_f32_e32 v178, v180, v181
	v_sub_f32_e32 v179, v182, v183
	v_add_f32_e32 v180, v170, v171
	v_add_f32_e32 v174, v176, v177
	v_cvt_pk_bf16_f32 v170, v140, v157
	v_cvt_pk_bf16_f32 v171, v178, v179
	v_cvt_pk_bf16_f32 v172, v180, v172
	v_cvt_pk_bf16_f32 v173, v173, v174
	global_store_dwordx4 v[162:163], v[170:173], off
	global_load_dword v140, v[158:159], off offset:512
	v_mov_b32_e32 v174, v62
	v_mov_b32_e32 v170, v60
	v_mov_b32_e32 v171, v56
	v_mov_b32_e32 v172, v61
	v_mov_b32_e32 v173, v57
	v_mov_b32_e32 v175, v58
	v_mov_b32_e32 v176, v63
	v_mov_b32_e32 v177, v59
	v_add_co_u32_e32 v162, vcc, s31, v160
	s_movk_i32 s31, 0x4000
	s_nop 0
	v_addc_co_u32_e32 v163, vcc, 0, v161, vcc
	s_nop 1
	v_add_co_u32_e32 v160, vcc, s31, v160
	s_waitcnt vmcnt(0)
; __device__ __forceinline__ void sincos_rr(float ang, float& s, float& c) {
;     const float k = rintf(ang * 0.15915494309189535f);
;     float r = fmaf(-k, 6.2831854820251465f, ang);
;     r = fmaf(-k, -1.7484555e-7f, r);
;     const float rev = r * 0.15915494309189535f;
;     s = __builtin_amdgcn_sinf(rev); c = __builtin_amdgcn_cosf(rev);
; }
;     __device__ __forceinline__ void operator()(const f32x4 (&acc)[2][2][4][2], const Unit& u, int wr, int wc, int fr, int fq) const {
;     ...
;         } else if (wc < 2) {
;             const f32x4 invf = *(const f32x4*)(INVF64 + 16 * wc + 4 * fq);
; #pragma unroll
;             for (int ai = 0; ai < 2; ++ai)
; #pragma unroll
;                 for (int m = 0; m < 4; ++m) { const int row = row0 + ai * HALF + m * 16; const float p = (float)pos[row]; f32x4 o0, o1;
; #pragma unroll
;                     for (int e = 0; e < 4; ++e) { float s, c; sincos_rr(p * invf[e], s, c);
;                         const float x1 = acc[ai][0][m][0][e], x2 = acc[ai][0][m][1][e];
;                         o0[e] = x1 * c - x2 * s; o1[e] = x2 * c + x1 * s; }
;                     st8(KR + (size_t)row * 64 + cl, o0, o1); }
	v_cvt_f32_i32_e32 v140, v140
	v_addc_co_u32_e32 v161, vcc, 0, v161, vcc
	v_mul_f32_e32 v178, v129, v140
	v_mul_f32_e32 v179, v130, v140
	v_mul_f32_e32 v157, v128, v140
	v_mul_f32_e32 v140, v131, v140
	v_mul_f32_e32 v181, 0.15915494, v178
	v_mul_f32_e32 v182, 0.15915494, v179
	v_mul_f32_e32 v180, 0.15915494, v157
	v_mul_f32_e32 v183, 0.15915494, v140
	v_rndne_f32_e32 v181, v181
	v_rndne_f32_e32 v182, v182
	v_rndne_f32_e32 v180, v180
	v_rndne_f32_e32 v183, v183
	v_fmac_f32_e32 v178, 0xc0c90fdb, v181
	v_fmac_f32_e32 v179, 0xc0c90fdb, v182
	v_fmac_f32_e32 v157, 0xc0c90fdb, v180
	v_fmac_f32_e32 v140, 0xc0c90fdb, v183
	v_fmac_f32_e32 v178, 0x343bbd2e, v181
	v_fmac_f32_e32 v179, 0x343bbd2e, v182
	v_fmac_f32_e32 v157, 0x343bbd2e, v180
	v_fmac_f32_e32 v140, 0x343bbd2e, v183
	v_mul_f32_e32 v180, 0.15915494, v178
	v_mul_f32_e32 v182, 0.15915494, v179
	v_mul_f32_e32 v157, 0.15915494, v157
	v_mul_f32_e32 v140, 0.15915494, v140
	v_sin_f32_e32 v181, v180
	v_cos_f32_e32 v180, v180
	v_sin_f32_e32 v183, v182
	v_cos_f32_e32 v182, v182
	v_sin_f32_e32 v179, v157
	v_cos_f32_e32 v178, v157
	v_sin_f32_e32 v185, v140
	v_cos_f32_e32 v184, v140
	v_mov_b32_e32 v190, v181
	v_mov_b32_e32 v191, v180
	v_mov_b32_e32 v192, v183
	v_mov_b32_e32 v193, v182
	v_pk_mul_f32 v[186:187], v[170:171], v[178:179]
	v_mov_b32_e32 v188, v179
	v_mov_b32_e32 v189, v178
	v_pk_mul_f32 v[178:179], v[172:173], v[180:181]
	v_pk_mul_f32 v[180:181], v[174:175], v[182:183]
	v_mov_b32_e32 v194, v185
	v_mov_b32_e32 v195, v184
	v_pk_mul_f32 v[172:173], v[172:173], v[190:191]
	v_pk_mul_f32 v[174:175], v[174:175], v[192:193]
	v_pk_mul_f32 v[182:183], v[176:177], v[184:185]
	v_pk_mul_f32 v[170:171], v[170:171], v[188:189]
	v_pk_mul_f32 v[176:177], v[176:177], v[194:195]
	v_add_f32_e32 v172, v172, v173
	v_add_f32_e32 v173, v174, v175
	v_sub_f32_e32 v140, v186, v187
	v_sub_f32_e32 v157, v178, v179
	v_sub_f32_e32 v178, v180, v181
	v_sub_f32_e32 v179, v182, v183
	v_add_f32_e32 v180, v170, v171
	v_add_f32_e32 v174, v176, v177
	v_cvt_pk_bf16_f32 v170, v140, v157
	v_cvt_pk_bf16_f32 v171, v178, v179
	v_cvt_pk_bf16_f32 v172, v180, v172
	v_cvt_pk_bf16_f32 v173, v173, v174
	global_store_dwordx4 v[162:163], v[170:173], off offset:-4096
	global_load_dword v140, v[158:159], off offset:576
	v_mov_b32_e32 v174, v46
	v_mov_b32_e32 v170, v44
	v_mov_b32_e32 v171, v40
	v_mov_b32_e32 v172, v45
	v_mov_b32_e32 v173, v41
	v_mov_b32_e32 v175, v42
	v_mov_b32_e32 v176, v47
	v_mov_b32_e32 v177, v43
	s_waitcnt vmcnt(0)
	v_cvt_f32_i32_e32 v140, v140
	v_mul_f32_e32 v178, v129, v140
	v_mul_f32_e32 v179, v130, v140
	v_mul_f32_e32 v157, v128, v140
	v_mul_f32_e32 v140, v131, v140
	v_mul_f32_e32 v181, 0.15915494, v178
	v_mul_f32_e32 v182, 0.15915494, v179
	v_mul_f32_e32 v180, 0.15915494, v157
	v_mul_f32_e32 v183, 0.15915494, v140
	v_rndne_f32_e32 v181, v181
	v_rndne_f32_e32 v182, v182
	v_rndne_f32_e32 v180, v180
	v_rndne_f32_e32 v183, v183
	v_fmac_f32_e32 v178, 0xc0c90fdb, v181
	v_fmac_f32_e32 v179, 0xc0c90fdb, v182
	v_fmac_f32_e32 v157, 0xc0c90fdb, v180
	v_fmac_f32_e32 v140, 0xc0c90fdb, v183
	v_fmac_f32_e32 v178, 0x343bbd2e, v181
	v_fmac_f32_e32 v179, 0x343bbd2e, v182
	v_fmac_f32_e32 v157, 0x343bbd2e, v180
	v_fmac_f32_e32 v140, 0x343bbd2e, v183
	v_mul_f32_e32 v180, 0.15915494, v178
	v_mul_f32_e32 v182, 0.15915494, v179
	v_mul_f32_e32 v157, 0.15915494, v157
	v_mul_f32_e32 v140, 0.15915494, v140
	v_sin_f32_e32 v181, v180
	v_cos_f32_e32 v180, v180
	v_sin_f32_e32 v183, v182
	v_cos_f32_e32 v182, v182
	v_sin_f32_e32 v179, v157
	v_cos_f32_e32 v178, v157
	v_sin_f32_e32 v185, v140
	v_cos_f32_e32 v184, v140
	v_mov_b32_e32 v190, v181
	v_mov_b32_e32 v191, v180
	v_mov_b32_e32 v192, v183
	v_mov_b32_e32 v193, v182
	v_pk_mul_f32 v[186:187], v[170:171], v[178:179]
	v_mov_b32_e32 v188, v179
	v_mov_b32_e32 v189, v178
	v_pk_mul_f32 v[178:179], v[172:173], v[180:181]
	v_pk_mul_f32 v[180:181], v[174:175], v[182:183]
	v_mov_b32_e32 v194, v185
	v_mov_b32_e32 v195, v184
	v_pk_mul_f32 v[172:173], v[172:173], v[190:191]
	v_pk_mul_f32 v[174:175], v[174:175], v[192:193]
	v_pk_mul_f32 v[182:183], v[176:177], v[184:185]
	v_pk_mul_f32 v[170:171], v[170:171], v[188:189]
	v_pk_mul_f32 v[176:177], v[176:177], v[194:195]
	v_add_f32_e32 v172, v172, v173
	v_add_f32_e32 v173, v174, v175
	v_sub_f32_e32 v140, v186, v187
	v_sub_f32_e32 v157, v178, v179
	v_sub_f32_e32 v178, v180, v181
	v_sub_f32_e32 v179, v182, v183
	v_add_f32_e32 v180, v170, v171
	v_add_f32_e32 v174, v176, v177
	v_cvt_pk_bf16_f32 v170, v140, v157
	v_cvt_pk_bf16_f32 v171, v178, v179
	v_cvt_pk_bf16_f32 v172, v180, v172
	v_cvt_pk_bf16_f32 v173, v173, v174
	global_store_dwordx4 v[160:161], v[170:173], off offset:2048
	global_load_dword v140, v[158:159], off offset:640
	v_mov_b32_e32 v160, v28
	v_mov_b32_e32 v161, v24
	v_mov_b32_e32 v170, v29
	v_mov_b32_e32 v171, v25
	v_mov_b32_e32 v172, v30
	v_mov_b32_e32 v173, v26
	v_mov_b32_e32 v174, v31
	v_mov_b32_e32 v175, v27
	s_waitcnt vmcnt(0)
; __device__ __forceinline__ void sincos_rr(float ang, float& s, float& c) {
;     const float k = rintf(ang * 0.15915494309189535f);
;     float r = fmaf(-k, 6.2831854820251465f, ang);
;     r = fmaf(-k, -1.7484555e-7f, r);
;     const float rev = r * 0.15915494309189535f;
;     s = __builtin_amdgcn_sinf(rev); c = __builtin_amdgcn_cosf(rev);
; }
;     __device__ __forceinline__ void operator()(const f32x4 (&acc)[2][2][4][2], const Unit& u, int wr, int wc, int fr, int fq) const {
;     ...
;         } else if (wc < 2) {
;             const f32x4 invf = *(const f32x4*)(INVF64 + 16 * wc + 4 * fq);
; #pragma unroll
;             for (int ai = 0; ai < 2; ++ai)
; #pragma unroll
;                 for (int m = 0; m < 4; ++m) { const int row = row0 + ai * HALF + m * 16; const float p = (float)pos[row]; f32x4 o0, o1;
; #pragma unroll
;                     for (int e = 0; e < 4; ++e) { float s, c; sincos_rr(p * invf[e], s, c);
;                         const float x1 = acc[ai][0][m][0][e], x2 = acc[ai][0][m][1][e];
;                         o0[e] = x1 * c - x2 * s; o1[e] = x2 * c + x1 * s; }
;                     st8(KR + (size_t)row * 64 + cl, o0, o1); }
	v_cvt_f32_i32_e32 v140, v140
	v_mul_f32_e32 v177, v130, v140
	v_mul_f32_e32 v157, v128, v140
	v_mul_f32_e32 v176, v129, v140
	v_mul_f32_e32 v140, v131, v140
	v_mul_f32_e32 v180, 0.15915494, v177
	v_mul_f32_e32 v178, 0.15915494, v157
	v_mul_f32_e32 v179, 0.15915494, v176
	v_mul_f32_e32 v181, 0.15915494, v140
	v_rndne_f32_e32 v180, v180
	v_rndne_f32_e32 v178, v178
	v_rndne_f32_e32 v179, v179
	v_rndne_f32_e32 v181, v181
	v_fmac_f32_e32 v177, 0xc0c90fdb, v180
	v_fmac_f32_e32 v157, 0xc0c90fdb, v178
	v_fmac_f32_e32 v176, 0xc0c90fdb, v179
	v_fmac_f32_e32 v140, 0xc0c90fdb, v181
	v_fmac_f32_e32 v177, 0x343bbd2e, v180
	v_fmac_f32_e32 v157, 0x343bbd2e, v178
	v_fmac_f32_e32 v176, 0x343bbd2e, v179
	v_fmac_f32_e32 v140, 0x343bbd2e, v181
	v_mul_f32_e32 v180, 0.15915494, v177
	v_mul_f32_e32 v157, 0.15915494, v157
	v_mul_f32_e32 v178, 0.15915494, v176
	v_mul_f32_e32 v140, 0.15915494, v140
	v_sin_f32_e32 v181, v180
	v_cos_f32_e32 v180, v180
	v_sin_f32_e32 v177, v157
	v_cos_f32_e32 v176, v157
	v_sin_f32_e32 v179, v178
	v_cos_f32_e32 v178, v178
	v_sin_f32_e32 v183, v140
	v_cos_f32_e32 v182, v140
	v_mov_b32_e32 v190, v181
	v_mov_b32_e32 v191, v180
	v_pk_mul_f32 v[184:185], v[160:161], v[176:177]
	v_mov_b32_e32 v186, v177
	v_mov_b32_e32 v187, v176
	v_pk_mul_f32 v[176:177], v[170:171], v[178:179]
	v_mov_b32_e32 v188, v179
	v_mov_b32_e32 v189, v178
	v_pk_mul_f32 v[178:179], v[172:173], v[180:181]
	v_mov_b32_e32 v192, v183
	v_mov_b32_e32 v193, v182
	v_pk_mul_f32 v[172:173], v[172:173], v[190:191]
	v_pk_mul_f32 v[180:181], v[174:175], v[182:183]
	v_pk_mul_f32 v[160:161], v[160:161], v[186:187]
	v_pk_mul_f32 v[170:171], v[170:171], v[188:189]
	v_pk_mul_f32 v[174:175], v[174:175], v[192:193]
	v_add_f32_e32 v173, v172, v173
	v_sub_f32_e32 v140, v184, v185
	v_sub_f32_e32 v157, v176, v177
	v_sub_f32_e32 v176, v178, v179
	v_sub_f32_e32 v177, v180, v181
	v_add_f32_e32 v160, v160, v161
	v_add_f32_e32 v161, v170, v171
	v_add_f32_e32 v174, v174, v175
	v_cvt_pk_bf16_f32 v170, v140, v157
	v_cvt_pk_bf16_f32 v171, v176, v177
	v_cvt_pk_bf16_f32 v172, v160, v161
	v_cvt_pk_bf16_f32 v173, v173, v174
	global_store_dwordx4 v[162:163], v[170:173], off
	global_load_dword v140, v[158:159], off offset:704
	v_mov_b32_e32 v158, v12
	v_mov_b32_e32 v159, v8
	v_mov_b32_e32 v160, v13
	v_mov_b32_e32 v161, v9
	v_mov_b32_e32 v170, v14
	v_mov_b32_e32 v171, v10
	v_mov_b32_e32 v172, v15
	v_mov_b32_e32 v173, v11
	s_waitcnt vmcnt(0)
	v_cvt_f32_i32_e32 v140, v140
	v_mul_f32_e32 v128, v128, v140
	v_mul_f32_e32 v129, v129, v140
	v_mul_f32_e32 v130, v130, v140
	v_mul_f32_e32 v131, v131, v140
	v_mul_f32_e32 v140, 0.15915494, v128
	v_mul_f32_e32 v157, 0.15915494, v129
	v_mul_f32_e32 v174, 0.15915494, v130
	v_mul_f32_e32 v175, 0.15915494, v131
	v_rndne_f32_e32 v140, v140
	v_rndne_f32_e32 v157, v157
	v_rndne_f32_e32 v174, v174
	v_rndne_f32_e32 v175, v175
	v_fmac_f32_e32 v128, 0xc0c90fdb, v140
	v_fmac_f32_e32 v129, 0xc0c90fdb, v157
	v_fmac_f32_e32 v130, 0xc0c90fdb, v174
	v_fmac_f32_e32 v131, 0xc0c90fdb, v175
	v_fmac_f32_e32 v128, 0x343bbd2e, v140
	v_fmac_f32_e32 v129, 0x343bbd2e, v157
	v_fmac_f32_e32 v130, 0x343bbd2e, v174
	v_fmac_f32_e32 v131, 0x343bbd2e, v175
	v_mul_f32_e32 v128, 0.15915494, v128
	v_mul_f32_e32 v140, 0.15915494, v129
	v_mul_f32_e32 v157, 0.15915494, v130
	v_mul_f32_e32 v176, 0.15915494, v131
	v_sin_f32_e32 v129, v128
	v_cos_f32_e32 v128, v128
	v_sin_f32_e32 v131, v140
	v_cos_f32_e32 v130, v140
	v_sin_f32_e32 v175, v157
	v_cos_f32_e32 v174, v157
	v_sin_f32_e32 v177, v176
	v_cos_f32_e32 v176, v176
	v_pk_mul_f32 v[178:179], v[158:159], v[128:129]
	v_mov_b32_e32 v180, v129
	v_mov_b32_e32 v181, v128
	v_pk_mul_f32 v[128:129], v[160:161], v[130:131]
	v_mov_b32_e32 v182, v131
	v_mov_b32_e32 v183, v130
	v_pk_mul_f32 v[130:131], v[170:171], v[174:175]
	v_mov_b32_e32 v184, v175
	v_mov_b32_e32 v185, v174
	v_pk_mul_f32 v[174:175], v[172:173], v[176:177]
	v_mov_b32_e32 v186, v177
	v_mov_b32_e32 v187, v176
	v_sub_f32_e32 v176, v130, v131
	v_pk_mul_f32 v[130:131], v[170:171], v[184:185]
	v_pk_mul_f32 v[158:159], v[158:159], v[180:181]
	v_sub_f32_e32 v157, v128, v129
	v_pk_mul_f32 v[128:129], v[160:161], v[182:183]
	v_pk_mul_f32 v[160:161], v[172:173], v[186:187]
	v_add_f32_e32 v131, v130, v131
	v_sub_f32_e32 v140, v178, v179
	v_sub_f32_e32 v170, v174, v175
	v_add_f32_e32 v158, v158, v159
	v_add_f32_e32 v159, v128, v129
	v_add_f32_e32 v160, v160, v161
	v_cvt_pk_bf16_f32 v128, v140, v157
	v_cvt_pk_bf16_f32 v129, v176, v170
	v_cvt_pk_bf16_f32 v130, v158, v159
	v_cvt_pk_bf16_f32 v131, v131, v160
	global_store_dwordx4 v[162:163], v[128:131], off offset:2048

; __device__ __forceinline__ unsigned cvt_pk_bf16(float lo, float hi) { unsigned r; asm volatile("v_cvt_pk_bf16_f32 %0, %1, %2" : "=v"(r) : "v"(lo), "v"(hi)); return r; }
; __device__ __forceinline__ float silu_f(float v) { return v / (1.0f + __expf(-v)); }
; __device__ __forceinline__ void st8(bf16_t* p, f32x4 v0, f32x4 v1) {
;     u32x4 w; w.x = cvt_pk_bf16(v0[0], v0[1]); w.y = cvt_pk_bf16(v0[2], v0[3]); w.z = cvt_pk_bf16(v1[0], v1[1]); w.w = cvt_pk_bf16(v1[2], v1[3]);
;     *(u32x4*)p = w;
; }
; __device__ __forceinline__ f32x4 silu4(f32x4 v) { f32x4 o; o[0] = silu_f(v[0]); o[1] = silu_f(v[1]); o[2] = silu_f(v[2]); o[3] = silu_f(v[3]); return o; }
;     __device__ __forceinline__ void operator()(const f32x4 (&acc)[2][2][4][2], const Unit& u, int wr, int wc, int fr, int fq) const {
;     ...
;             bf16_t* base = SG1 + (u.pn - 4) * 256 + cl;
; #pragma unroll
;             for (int ai = 0; ai < 2; ++ai)
; #pragma unroll
;                 for (int m = 0; m < 4; ++m) { bf16_t* rowp = base + (size_t)(row0 + ai * HALF + m * 16) * 2048;
; #pragma unroll
;                     for (int bj = 0; bj < 2; ++bj) st8(rowp + bj * HALF, silu4(acc[ai][bj][m][0]), silu4(acc[ai][bj][m][1])); }
.LBB0_776:
	s_andn2_b64 vcc, exec, s[36:37]
	s_cbranch_vccnz .LBB0_778
	v_mul_f32_e32 v128, 0xbfb8aa3b, v124
	v_exp_f32_e32 v157, v128
	s_lshl_b32 s31, s46, 9
	s_add_u32 s36, s90, s31
	s_addc_u32 s37, s91, 0
	v_lshlrev_b32_e32 v140, 1, v142
	v_lshl_add_u64 v[128:129], s[36:37], 0, v[140:141]
	s_mov_b64 s[36:37], 0x127ff800
	v_add_f32_e32 v140, 1.0, v157
	v_lshl_add_u64 v[130:131], v[128:129], 0, s[36:37]
	v_rcp_f32_e32 v159, v140
	v_ashrrev_i32_e32 v157, 31, v156
	v_lshlrev_b64 v[128:129], 12, v[156:157]
	v_mul_f32_e32 v161, 0xbfb8aa3b, v125
	v_exp_f32_e32 v161, v161
	s_nop 0
	v_add_f32_e32 v158, 1.0, v161
	v_rcp_f32_e32 v162, v158
	v_mul_f32_e32 v157, v124, v159
	v_mul_f32_e32 v160, 0xbfb8aa3b, v126
	v_mov_b32_e32 v140, v157
	v_exp_f32_e32 v160, v160
	s_nop 0
	v_add_f32_e32 v160, 1.0, v160
	v_rcp_f32_e32 v163, v160
	v_mul_f32_e32 v157, v125, v162
	v_mul_f32_e32 v162, 0xbfb8aa3b, v127
	v_exp_f32_e32 v162, v162
	s_nop 0
	v_add_f32_e32 v161, 1.0, v162
	v_rcp_f32_e32 v170, v161
	v_mul_f32_e32 v158, v126, v163
	v_mov_b32_e32 v159, v158
	v_mul_f32_e32 v163, 0xbfb8aa3b, v120
	v_exp_f32_e32 v163, v163
	s_nop 0
	v_add_f32_e32 v162, 1.0, v163
	v_rcp_f32_e32 v171, v162
	v_mul_f32_e32 v158, v127, v170
	v_mov_b32_e32 v160, v158
	v_mul_f32_e32 v170, 0xbfb8aa3b, v121
	v_exp_f32_e32 v170, v170
	s_nop 0
	v_add_f32_e32 v163, 1.0, v170
	v_rcp_f32_e32 v172, v163
	v_mul_f32_e32 v158, v120, v171
	v_mov_b32_e32 v161, v158
	v_mul_f32_e32 v171, 0xbfb8aa3b, v122
	v_exp_f32_e32 v171, v171
	s_nop 0
	v_add_f32_e32 v170, 1.0, v171
	v_rcp_f32_e32 v173, v170
	v_mul_f32_e32 v158, v121, v172
	v_mov_b32_e32 v162, v158
	v_mul_f32_e32 v172, 0xbfb8aa3b, v123
	v_exp_f32_e32 v172, v172
	s_nop 0
	v_add_f32_e32 v171, 1.0, v172
	v_rcp_f32_e32 v174, v171
	v_mul_f32_e32 v158, v122, v173
	v_mov_b32_e32 v163, v158
	v_lshl_add_u64 v[128:129], v[130:131], 0, v[128:129]
	v_mul_f32_e32 v158, v123, v174
	v_mul_f32_e32 v170, 0xbfb8aa3b, v116
	v_exp_f32_e32 v170, v170
	v_mov_b32_e32 v171, v158
	v_cvt_pk_bf16_f32 v158, v140, v157
	v_cvt_pk_bf16_f32 v159, v159, v160
	v_add_f32_e32 v140, 1.0, v170
	v_rcp_f32_e32 v170, v140
	v_cvt_pk_bf16_f32 v160, v161, v162
	v_cvt_pk_bf16_f32 v161, v163, v171
	global_store_dwordx4 v[128:129], v[158:161], off
	v_mul_f32_e32 v162, 0xbfb8aa3b, v118
	v_exp_f32_e32 v162, v162
	v_mul_f32_e32 v160, 0xbfb8aa3b, v117
	v_exp_f32_e32 v160, v160
	s_nop 0
	v_add_f32_e32 v158, 1.0, v160
	v_rcp_f32_e32 v161, v158
	v_mul_f32_e32 v157, v116, v170
	v_mov_b32_e32 v140, v157
	v_add_f32_e32 v160, 1.0, v162
	v_rcp_f32_e32 v163, v160
	v_mul_f32_e32 v157, v117, v161
	v_mul_f32_e32 v161, 0xbfb8aa3b, v119
	v_exp_f32_e32 v161, v161
	s_nop 0
	v_add_f32_e32 v161, 1.0, v161
	v_rcp_f32_e32 v170, v161
	v_mul_f32_e32 v158, v118, v163
	v_mov_b32_e32 v159, v158
	v_mul_f32_e32 v163, 0xbfb8aa3b, v112
	v_exp_f32_e32 v163, v163
	s_nop 0
	v_add_f32_e32 v162, 1.0, v163
	v_rcp_f32_e32 v171, v162
	v_mul_f32_e32 v158, v119, v170
	v_mov_b32_e32 v160, v158
	v_mul_f32_e32 v170, 0xbfb8aa3b, v113
	v_exp_f32_e32 v170, v170
	s_nop 0
	v_add_f32_e32 v163, 1.0, v170
	v_rcp_f32_e32 v172, v163
	v_mul_f32_e32 v158, v112, v171
	v_mov_b32_e32 v161, v158
	v_mul_f32_e32 v171, 0xbfb8aa3b, v114
	v_exp_f32_e32 v171, v171
	s_nop 0
	v_add_f32_e32 v170, 1.0, v171
	v_rcp_f32_e32 v173, v170
	v_mul_f32_e32 v158, v113, v172
	v_mov_b32_e32 v162, v158
	v_mul_f32_e32 v172, 0xbfb8aa3b, v115
	v_exp_f32_e32 v172, v172
	s_nop 0
	v_add_f32_e32 v171, 1.0, v172
	v_rcp_f32_e32 v174, v171
	v_mul_f32_e32 v158, v114, v173
	v_mov_b32_e32 v163, v158
	v_mul_f32_e32 v158, v115, v174
	v_mov_b32_e32 v170, v158
	v_cvt_pk_bf16_f32 v158, v140, v157
	v_mul_f32_e32 v140, 0xbfb8aa3b, v108
	v_exp_f32_e32 v140, v140
	v_cvt_pk_bf16_f32 v159, v159, v160
	v_cvt_pk_bf16_f32 v160, v161, v162
	v_cvt_pk_bf16_f32 v161, v163, v170
	global_store_dwordx4 v[128:129], v[158:161], off offset:256
	s_nop 0
	v_add_f32_e32 v140, 1.0, v140
	v_rcp_f32_e32 v160, v140
	v_mul_f32_e32 v163, 0xbfb8aa3b, v109
	v_exp_f32_e32 v163, v163
	v_or_b32_e32 v158, 16, v156
	v_add_f32_e32 v161, 1.0, v163
	v_rcp_f32_e32 v170, v161
	v_mul_f32_e32 v157, v108, v160
	v_mul_f32_e32 v162, 0xbfb8aa3b, v110
	v_mov_b32_e32 v140, v157
	v_exp_f32_e32 v162, v162
	s_nop 0
	v_add_f32_e32 v162, 1.0, v162
	v_rcp_f32_e32 v171, v162
	v_mul_f32_e32 v157, v109, v170
	v_mul_f32_e32 v170, 0xbfb8aa3b, v111
	v_exp_f32_e32 v170, v170
	s_nop 0
	v_add_f32_e32 v163, 1.0, v170
	v_rcp_f32_e32 v172, v163
	v_mul_f32_e32 v160, v110, v171
	v_mov_b32_e32 v161, v160
	v_mul_f32_e32 v171, 0xbfb8aa3b, v104
	v_exp_f32_e32 v171, v171
	s_nop 0
	v_add_f32_e32 v170, 1.0, v171
	v_rcp_f32_e32 v173, v170
	v_mul_f32_e32 v160, v111, v172
	v_mov_b32_e32 v162, v160
	v_mul_f32_e32 v172, 0xbfb8aa3b, v105
	v_exp_f32_e32 v172, v172
	s_nop 0
	v_add_f32_e32 v171, 1.0, v172
	v_rcp_f32_e32 v174, v171
	v_mul_f32_e32 v160, v104, v173
	v_mov_b32_e32 v163, v160
	v_mul_f32_e32 v173, 0xbfb8aa3b, v106
	v_exp_f32_e32 v173, v173
	s_nop 0
	v_add_f32_e32 v172, 1.0, v173
	v_rcp_f32_e32 v175, v172
	v_mul_f32_e32 v160, v105, v174
	v_mov_b32_e32 v170, v160
	v_mul_f32_e32 v174, 0xbfb8aa3b, v107
	v_exp_f32_e32 v174, v174
	s_nop 0
	v_add_f32_e32 v173, 1.0, v174
	v_rcp_f32_e32 v176, v173
	v_mul_f32_e32 v160, v106, v175
	v_mov_b32_e32 v171, v160
	v_ashrrev_i32_e32 v159, 31, v158
	v_mul_f32_e32 v160, v107, v176
	v_mul_f32_e32 v172, 0xbfb8aa3b, v100
	v_exp_f32_e32 v172, v172
	v_mov_b32_e32 v173, v160
	v_cvt_pk_bf16_f32 v160, v140, v157
	v_lshlrev_b64 v[158:159], 12, v[158:159]
	v_add_f32_e32 v140, 1.0, v172
	v_rcp_f32_e32 v172, v140
	v_lshl_add_u64 v[158:159], v[130:131], 0, v[158:159]
	v_cvt_pk_bf16_f32 v161, v161, v162
	v_cvt_pk_bf16_f32 v162, v163, v170
; __device__ __forceinline__ unsigned cvt_pk_bf16(float lo, float hi) { unsigned r; asm volatile("v_cvt_pk_bf16_f32 %0, %1, %2" : "=v"(r) : "v"(lo), "v"(hi)); return r; }
; __device__ __forceinline__ float silu_f(float v) { return v / (1.0f + __expf(-v)); }
; __device__ __forceinline__ void st8(bf16_t* p, f32x4 v0, f32x4 v1) {
;     u32x4 w; w.x = cvt_pk_bf16(v0[0], v0[1]); w.y = cvt_pk_bf16(v0[2], v0[3]); w.z = cvt_pk_bf16(v1[0], v1[1]); w.w = cvt_pk_bf16(v1[2], v1[3]);
;     *(u32x4*)p = w;
; }
; __device__ __forceinline__ f32x4 silu4(f32x4 v) { f32x4 o; o[0] = silu_f(v[0]); o[1] = silu_f(v[1]); o[2] = silu_f(v[2]); o[3] = silu_f(v[3]); return o; }
;     __device__ __forceinline__ void operator()(const f32x4 (&acc)[2][2][4][2], const Unit& u, int wr, int wc, int fr, int fq) const {
;     ...
;             bf16_t* base = SG1 + (u.pn - 4) * 256 + cl;
; #pragma unroll
;             for (int ai = 0; ai < 2; ++ai)
; #pragma unroll
;                 for (int m = 0; m < 4; ++m) { bf16_t* rowp = base + (size_t)(row0 + ai * HALF + m * 16) * 2048;
; #pragma unroll
;                     for (int bj = 0; bj < 2; ++bj) st8(rowp + bj * HALF, silu4(acc[ai][bj][m][0]), silu4(acc[ai][bj][m][1])); }
	v_cvt_pk_bf16_f32 v163, v171, v173
	global_store_dwordx4 v[158:159], v[160:163], off
	v_mul_f32_e32 v170, 0xbfb8aa3b, v102
	v_exp_f32_e32 v170, v170
	v_mul_f32_e32 v162, 0xbfb8aa3b, v101
	v_exp_f32_e32 v162, v162
	s_nop 0
	v_add_f32_e32 v160, 1.0, v162
	v_rcp_f32_e32 v163, v160
	v_mul_f32_e32 v157, v100, v172
	v_mov_b32_e32 v140, v157
	v_add_f32_e32 v162, 1.0, v170
	v_rcp_f32_e32 v171, v162
	v_mul_f32_e32 v157, v101, v163
	v_mul_f32_e32 v163, 0xbfb8aa3b, v103
	v_exp_f32_e32 v163, v163
	s_nop 0
	v_add_f32_e32 v163, 1.0, v163
	v_rcp_f32_e32 v172, v163
	v_mul_f32_e32 v160, v102, v171
	v_mov_b32_e32 v161, v160
	v_mul_f32_e32 v171, 0xbfb8aa3b, v96
	v_exp_f32_e32 v171, v171
	s_nop 0
	v_add_f32_e32 v170, 1.0, v171
	v_rcp_f32_e32 v173, v170
	v_mul_f32_e32 v160, v103, v172
	v_mov_b32_e32 v162, v160
	v_mul_f32_e32 v172, 0xbfb8aa3b, v97
	v_exp_f32_e32 v172, v172
	s_nop 0
	v_add_f32_e32 v171, 1.0, v172
	v_rcp_f32_e32 v174, v171
	v_mul_f32_e32 v160, v96, v173
	v_mov_b32_e32 v163, v160
	v_mul_f32_e32 v173, 0xbfb8aa3b, v98
	v_exp_f32_e32 v173, v173
	s_nop 0
	v_add_f32_e32 v172, 1.0, v173
	v_rcp_f32_e32 v175, v172
	v_mul_f32_e32 v160, v97, v174
	v_mov_b32_e32 v170, v160
	v_mul_f32_e32 v174, 0xbfb8aa3b, v99
	v_exp_f32_e32 v174, v174
	s_nop 0
	v_add_f32_e32 v173, 1.0, v174
	v_rcp_f32_e32 v176, v173
	v_mul_f32_e32 v160, v98, v175
	v_mov_b32_e32 v171, v160
	v_mul_f32_e32 v160, v99, v176
	v_mov_b32_e32 v172, v160
	v_cvt_pk_bf16_f32 v160, v140, v157
	v_mul_f32_e32 v140, 0xbfb8aa3b, v92
	v_exp_f32_e32 v140, v140
	v_cvt_pk_bf16_f32 v161, v161, v162
	v_cvt_pk_bf16_f32 v162, v163, v170
	v_cvt_pk_bf16_f32 v163, v171, v172
	global_store_dwordx4 v[158:159], v[160:163], off offset:256
	s_nop 0
	v_add_f32_e32 v140, 1.0, v140
	v_rcp_f32_e32 v160, v140
	v_mul_f32_e32 v163, 0xbfb8aa3b, v93
	v_exp_f32_e32 v163, v163
	v_or_b32_e32 v158, 32, v156
	v_add_f32_e32 v161, 1.0, v163
	v_rcp_f32_e32 v170, v161
	v_mul_f32_e32 v157, v92, v160
	v_mul_f32_e32 v162, 0xbfb8aa3b, v94
	v_mov_b32_e32 v140, v157
	v_exp_f32_e32 v162, v162
	s_nop 0
	v_add_f32_e32 v162, 1.0, v162
	v_rcp_f32_e32 v171, v162
	v_mul_f32_e32 v157, v93, v170
	v_mul_f32_e32 v170, 0xbfb8aa3b, v95
	v_exp_f32_e32 v170, v170
	s_nop 0
	v_add_f32_e32 v163, 1.0, v170
	v_rcp_f32_e32 v172, v163
	v_mul_f32_e32 v160, v94, v171
	v_mov_b32_e32 v161, v160
	v_mul_f32_e32 v171, 0xbfb8aa3b, v88
	v_exp_f32_e32 v171, v171
	s_nop 0
	v_add_f32_e32 v170, 1.0, v171
	v_rcp_f32_e32 v173, v170
	v_mul_f32_e32 v160, v95, v172
	v_mov_b32_e32 v162, v160
	v_mul_f32_e32 v172, 0xbfb8aa3b, v89
	v_exp_f32_e32 v172, v172
	s_nop 0
	v_add_f32_e32 v171, 1.0, v172
	v_rcp_f32_e32 v174, v171
	v_mul_f32_e32 v160, v88, v173
	v_mov_b32_e32 v163, v160
	v_mul_f32_e32 v173, 0xbfb8aa3b, v90
	v_exp_f32_e32 v173, v173
	s_nop 0
	v_add_f32_e32 v172, 1.0, v173
	v_rcp_f32_e32 v175, v172
	v_mul_f32_e32 v160, v89, v174
	v_mov_b32_e32 v170, v160
	v_mul_f32_e32 v174, 0xbfb8aa3b, v91
	v_exp_f32_e32 v174, v174
	s_nop 0
	v_add_f32_e32 v173, 1.0, v174
	v_rcp_f32_e32 v176, v173
	v_mul_f32_e32 v160, v90, v175
	v_mov_b32_e32 v171, v160
	v_ashrrev_i32_e32 v159, 31, v158
	v_mul_f32_e32 v160, v91, v176
	v_mul_f32_e32 v172, 0xbfb8aa3b, v84
	v_exp_f32_e32 v172, v172
	v_mov_b32_e32 v173, v160
	v_cvt_pk_bf16_f32 v160, v140, v157
	v_lshlrev_b64 v[158:159], 12, v[158:159]
	v_add_f32_e32 v140, 1.0, v172
	v_rcp_f32_e32 v172, v140
	v_lshl_add_u64 v[158:159], v[130:131], 0, v[158:159]
	v_cvt_pk_bf16_f32 v161, v161, v162
	v_cvt_pk_bf16_f32 v162, v163, v170
	v_cvt_pk_bf16_f32 v163, v171, v173
	global_store_dwordx4 v[158:159], v[160:163], off
	v_mul_f32_e32 v170, 0xbfb8aa3b, v86
	v_exp_f32_e32 v170, v170
	v_mul_f32_e32 v162, 0xbfb8aa3b, v85
	v_exp_f32_e32 v162, v162
	s_nop 0
	v_add_f32_e32 v160, 1.0, v162
	v_rcp_f32_e32 v163, v160
	v_mul_f32_e32 v157, v84, v172
	v_mov_b32_e32 v140, v157
	v_add_f32_e32 v162, 1.0, v170
	v_rcp_f32_e32 v171, v162
	v_mul_f32_e32 v157, v85, v163
	v_mul_f32_e32 v163, 0xbfb8aa3b, v87
	v_exp_f32_e32 v163, v163
	s_nop 0
	v_add_f32_e32 v163, 1.0, v163
	v_rcp_f32_e32 v172, v163
	v_mul_f32_e32 v160, v86, v171
	v_mov_b32_e32 v161, v160
	v_mul_f32_e32 v171, 0xbfb8aa3b, v80
	v_exp_f32_e32 v171, v171
	s_nop 0
	v_add_f32_e32 v170, 1.0, v171
	v_rcp_f32_e32 v173, v170
	v_mul_f32_e32 v160, v87, v172
	v_mov_b32_e32 v162, v160
	v_mul_f32_e32 v172, 0xbfb8aa3b, v81
	v_exp_f32_e32 v172, v172
	s_nop 0
	v_add_f32_e32 v171, 1.0, v172
	v_rcp_f32_e32 v174, v171
	v_mul_f32_e32 v160, v80, v173
	v_mov_b32_e32 v163, v160
	v_mul_f32_e32 v173, 0xbfb8aa3b, v82
	v_exp_f32_e32 v173, v173
	s_nop 0
	v_add_f32_e32 v172, 1.0, v173
	v_rcp_f32_e32 v175, v172
	v_mul_f32_e32 v160, v81, v174
	v_mov_b32_e32 v170, v160
	v_mul_f32_e32 v174, 0xbfb8aa3b, v83
	v_exp_f32_e32 v174, v174
	s_nop 0
	v_add_f32_e32 v173, 1.0, v174
	v_rcp_f32_e32 v176, v173
	v_mul_f32_e32 v160, v82, v175
	v_mov_b32_e32 v171, v160
	v_mul_f32_e32 v160, v83, v176
	v_mov_b32_e32 v172, v160
	v_cvt_pk_bf16_f32 v160, v140, v157
	v_mul_f32_e32 v140, 0xbfb8aa3b, v76
	v_exp_f32_e32 v140, v140
	v_cvt_pk_bf16_f32 v161, v161, v162
	v_cvt_pk_bf16_f32 v162, v163, v170
	v_cvt_pk_bf16_f32 v163, v171, v172
	global_store_dwordx4 v[158:159], v[160:163], off offset:256
	s_nop 0
	v_add_f32_e32 v140, 1.0, v140
	v_rcp_f32_e32 v160, v140
	v_or_b32_e32 v158, 48, v156
	v_ashrrev_i32_e32 v159, 31, v158
	v_lshlrev_b64 v[158:159], 12, v[158:159]
	v_lshl_add_u64 v[130:131], v[130:131], 0, v[158:159]
	v_mul_f32_e32 v161, 0xbfb8aa3b, v77
	v_exp_f32_e32 v161, v161
	s_nop 0
	v_add_f32_e32 v158, 1.0, v161
	v_rcp_f32_e32 v162, v158
	v_mul_f32_e32 v157, v76, v160
	v_mul_f32_e32 v160, 0xbfb8aa3b, v78
	v_mov_b32_e32 v140, v157
	v_exp_f32_e32 v160, v160
	s_nop 0
	v_add_f32_e32 v160, 1.0, v160
; __device__ __forceinline__ f32x4 silu4(f32x4 v) { f32x4 o; o[0] = silu_f(v[0]); o[1] = silu_f(v[1]); o[2] = silu_f(v[2]); o[3] = silu_f(v[3]); return o; }
; __device__ __forceinline__ float silu_f(float v) { return v / (1.0f + __expf(-v)); }
;     __device__ __forceinline__ void operator()(const f32x4 (&acc)[2][2][4][2], const Unit& u, int wr, int wc, int fr, int fq) const {
;     ...
;         } else if (u.pn < 12) {
;             bf16_t* base = SG1 + (u.pn - 4) * 256 + cl;
; #pragma unroll
;             for (int ai = 0; ai < 2; ++ai)
; #pragma unroll
;                 for (int m = 0; m < 4; ++m) { bf16_t* rowp = base + (size_t)(row0 + ai * HALF + m * 16) * 2048;
; #pragma unroll
;                     for (int bj = 0; bj < 2; ++bj) st8(rowp + bj * HALF, silu4(acc[ai][bj][m][0]), silu4(acc[ai][bj][m][1])); }
	v_rcp_f32_e32 v163, v160
	v_mul_f32_e32 v157, v77, v162
	v_mul_f32_e32 v162, 0xbfb8aa3b, v79
	v_exp_f32_e32 v162, v162
	s_nop 0
	v_add_f32_e32 v161, 1.0, v162
	v_rcp_f32_e32 v170, v161
	v_mul_f32_e32 v158, v78, v163
	v_mov_b32_e32 v159, v158
	v_mul_f32_e32 v163, 0xbfb8aa3b, v72
	v_exp_f32_e32 v163, v163
	s_nop 0
	v_add_f32_e32 v162, 1.0, v163
	v_rcp_f32_e32 v171, v162
	v_mul_f32_e32 v158, v79, v170
	v_mov_b32_e32 v160, v158
	v_mul_f32_e32 v170, 0xbfb8aa3b, v73
	v_exp_f32_e32 v170, v170
	s_nop 0
	v_add_f32_e32 v163, 1.0, v170
	v_rcp_f32_e32 v172, v163
	v_mul_f32_e32 v158, v72, v171
	v_mov_b32_e32 v161, v158
	v_mul_f32_e32 v171, 0xbfb8aa3b, v74
	v_exp_f32_e32 v171, v171
	s_nop 0
	v_add_f32_e32 v170, 1.0, v171
	v_rcp_f32_e32 v173, v170
	v_mul_f32_e32 v158, v73, v172
	v_mov_b32_e32 v162, v158
	v_mul_f32_e32 v172, 0xbfb8aa3b, v75
	v_exp_f32_e32 v172, v172
	s_nop 0
	v_add_f32_e32 v171, 1.0, v172
	v_rcp_f32_e32 v174, v171
	v_mul_f32_e32 v158, v74, v173
	v_mov_b32_e32 v163, v158
	v_mul_f32_e32 v158, v75, v174
	v_mul_f32_e32 v170, 0xbfb8aa3b, v68
	v_exp_f32_e32 v170, v170
	v_mov_b32_e32 v171, v158
	v_cvt_pk_bf16_f32 v158, v140, v157
	v_cvt_pk_bf16_f32 v159, v159, v160
	v_add_f32_e32 v140, 1.0, v170
	v_rcp_f32_e32 v170, v140
	v_cvt_pk_bf16_f32 v160, v161, v162
	v_cvt_pk_bf16_f32 v161, v163, v171
	global_store_dwordx4 v[130:131], v[158:161], off
	v_mul_f32_e32 v162, 0xbfb8aa3b, v70
	v_exp_f32_e32 v162, v162
	v_mul_f32_e32 v160, 0xbfb8aa3b, v69
	v_exp_f32_e32 v160, v160
	s_nop 0
	v_add_f32_e32 v158, 1.0, v160
	v_rcp_f32_e32 v161, v158
	v_mul_f32_e32 v157, v68, v170
	v_mov_b32_e32 v140, v157
	v_add_f32_e32 v160, 1.0, v162
	v_rcp_f32_e32 v163, v160
	v_mul_f32_e32 v157, v69, v161
	v_mul_f32_e32 v161, 0xbfb8aa3b, v71
	v_exp_f32_e32 v161, v161
	s_nop 0
	v_add_f32_e32 v161, 1.0, v161
	v_rcp_f32_e32 v170, v161
	v_mul_f32_e32 v158, v70, v163
	v_mov_b32_e32 v159, v158
	v_mul_f32_e32 v163, 0xbfb8aa3b, v64
	v_exp_f32_e32 v163, v163
	s_nop 0
	v_add_f32_e32 v162, 1.0, v163
	v_rcp_f32_e32 v171, v162
	v_mul_f32_e32 v158, v71, v170
	v_mov_b32_e32 v160, v158
	v_mul_f32_e32 v170, 0xbfb8aa3b, v65
	v_exp_f32_e32 v170, v170
	s_nop 0
	v_add_f32_e32 v163, 1.0, v170
	v_rcp_f32_e32 v172, v163
	v_mul_f32_e32 v158, v64, v171
	v_mov_b32_e32 v161, v158
	v_mul_f32_e32 v171, 0xbfb8aa3b, v66
	v_exp_f32_e32 v171, v171
	s_nop 0
	v_add_f32_e32 v170, 1.0, v171
	v_rcp_f32_e32 v173, v170
	v_mul_f32_e32 v158, v65, v172
	v_mov_b32_e32 v162, v158
	v_mul_f32_e32 v172, 0xbfb8aa3b, v67
	v_exp_f32_e32 v172, v172
	s_nop 0
	v_add_f32_e32 v171, 1.0, v172
	v_rcp_f32_e32 v174, v171
	v_mul_f32_e32 v158, v66, v173
	v_mov_b32_e32 v163, v158
	v_mul_f32_e32 v158, v67, v174
	v_mov_b32_e32 v170, v158
	v_mul_f32_e32 v158, 0xbfb8aa3b, v60
	v_exp_f32_e32 v171, v158
	v_cvt_pk_bf16_f32 v158, v140, v157
	v_cvt_pk_bf16_f32 v159, v159, v160
	v_cvt_pk_bf16_f32 v160, v161, v162
	v_cvt_pk_bf16_f32 v161, v163, v170
	global_store_dwordx4 v[130:131], v[158:161], off offset:256
	v_add_f32_e32 v140, 1.0, v171
	v_rcp_f32_e32 v162, v140
	v_mul_f32_e32 v160, 0xbfb8aa3b, v61
	v_exp_f32_e32 v160, v160
	s_mov_b64 s[36:37], 0x80000
	v_add_f32_e32 v158, 1.0, v160
	v_lshl_add_u64 v[130:131], v[128:129], 0, s[36:37]
	v_rcp_f32_e32 v161, v158
	v_mul_f32_e32 v157, v60, v162
	v_mov_b32_e32 v140, v157
	v_mul_f32_e32 v162, 0xbfb8aa3b, v62
	v_exp_f32_e32 v162, v162
	s_nop 0
	v_add_f32_e32 v160, 1.0, v162
	v_rcp_f32_e32 v163, v160
	v_mul_f32_e32 v157, v61, v161
	v_mul_f32_e32 v161, 0xbfb8aa3b, v63
	v_exp_f32_e32 v161, v161
	s_nop 0
	v_add_f32_e32 v161, 1.0, v161
	v_rcp_f32_e32 v170, v161
	v_mul_f32_e32 v158, v62, v163
	v_mov_b32_e32 v159, v158
	v_mul_f32_e32 v163, 0xbfb8aa3b, v56
	v_exp_f32_e32 v163, v163
	s_nop 0
	v_add_f32_e32 v162, 1.0, v163
	v_rcp_f32_e32 v171, v162
	v_mul_f32_e32 v158, v63, v170
	v_mov_b32_e32 v160, v158
	v_mul_f32_e32 v170, 0xbfb8aa3b, v57
	v_exp_f32_e32 v170, v170
	s_nop 0
	v_add_f32_e32 v163, 1.0, v170
	v_rcp_f32_e32 v172, v163
	v_mul_f32_e32 v158, v56, v171
	v_mov_b32_e32 v161, v158
	v_mul_f32_e32 v171, 0xbfb8aa3b, v58
	v_exp_f32_e32 v171, v171
	s_nop 0
	v_add_f32_e32 v170, 1.0, v171
	v_rcp_f32_e32 v173, v170
	v_mul_f32_e32 v158, v57, v172
	v_mov_b32_e32 v162, v158
	v_mul_f32_e32 v172, 0xbfb8aa3b, v59
	v_exp_f32_e32 v172, v172
	s_nop 0
	v_add_f32_e32 v171, 1.0, v172
	v_rcp_f32_e32 v174, v171
	v_mul_f32_e32 v158, v58, v173
	v_mov_b32_e32 v163, v158
	v_mul_f32_e32 v158, v59, v174
	v_mov_b32_e32 v170, v158
	v_cvt_pk_bf16_f32 v158, v140, v157
	v_mul_f32_e32 v140, 0xbfb8aa3b, v52
	v_exp_f32_e32 v140, v140
	v_cvt_pk_bf16_f32 v159, v159, v160
	v_cvt_pk_bf16_f32 v160, v161, v162
	v_cvt_pk_bf16_f32 v161, v163, v170
	v_add_co_u32_e32 v162, vcc, s68, v128
	v_add_f32_e32 v140, 1.0, v140
	v_rcp_f32_e32 v170, v140
	v_addc_co_u32_e32 v163, vcc, 0, v129, vcc
	global_store_dwordx4 v[162:163], v[158:161], off
	v_mul_f32_e32 v162, 0xbfb8aa3b, v54
	v_exp_f32_e32 v162, v162
	v_mul_f32_e32 v160, 0xbfb8aa3b, v53
	v_exp_f32_e32 v160, v160
	s_nop 0
	v_add_f32_e32 v158, 1.0, v160
	v_rcp_f32_e32 v161, v158
	v_mul_f32_e32 v157, v52, v170
	v_mov_b32_e32 v140, v157
	v_add_f32_e32 v160, 1.0, v162
	v_rcp_f32_e32 v163, v160
	v_mul_f32_e32 v157, v53, v161
	v_mul_f32_e32 v161, 0xbfb8aa3b, v55
	v_exp_f32_e32 v161, v161
	s_nop 0
	v_add_f32_e32 v161, 1.0, v161
	v_rcp_f32_e32 v170, v161
	v_mul_f32_e32 v158, v54, v163
	v_mov_b32_e32 v159, v158
	v_mul_f32_e32 v163, 0xbfb8aa3b, v48
	v_exp_f32_e32 v163, v163
	s_nop 0
	v_add_f32_e32 v162, 1.0, v163
	v_rcp_f32_e32 v171, v162
	v_mul_f32_e32 v158, v55, v170
	v_mov_b32_e32 v160, v158
	v_mul_f32_e32 v170, 0xbfb8aa3b, v49
	v_exp_f32_e32 v170, v170
	s_nop 0
	v_add_f32_e32 v163, 1.0, v170
	v_rcp_f32_e32 v172, v163
; __device__ __forceinline__ f32x4 silu4(f32x4 v) { f32x4 o; o[0] = silu_f(v[0]); o[1] = silu_f(v[1]); o[2] = silu_f(v[2]); o[3] = silu_f(v[3]); return o; }
; __device__ __forceinline__ float silu_f(float v) { return v / (1.0f + __expf(-v)); }
;     __device__ __forceinline__ void operator()(const f32x4 (&acc)[2][2][4][2], const Unit& u, int wr, int wc, int fr, int fq) const {
;     ...
;         } else if (u.pn < 12) {
;             bf16_t* base = SG1 + (u.pn - 4) * 256 + cl;
; #pragma unroll
;             for (int ai = 0; ai < 2; ++ai)
; #pragma unroll
;                 for (int m = 0; m < 4; ++m) { bf16_t* rowp = base + (size_t)(row0 + ai * HALF + m * 16) * 2048;
; #pragma unroll
;                     for (int bj = 0; bj < 2; ++bj) st8(rowp + bj * HALF, silu4(acc[ai][bj][m][0]), silu4(acc[ai][bj][m][1])); }
	v_mul_f32_e32 v158, v48, v171
	v_mov_b32_e32 v161, v158
	v_mul_f32_e32 v171, 0xbfb8aa3b, v50
	v_exp_f32_e32 v171, v171
	s_nop 0
	v_add_f32_e32 v170, 1.0, v171
	v_rcp_f32_e32 v173, v170
	v_mul_f32_e32 v158, v49, v172
	v_mov_b32_e32 v162, v158
	v_mul_f32_e32 v172, 0xbfb8aa3b, v51
	v_exp_f32_e32 v172, v172
	s_nop 0
	v_add_f32_e32 v171, 1.0, v172
	v_rcp_f32_e32 v174, v171
	v_mul_f32_e32 v158, v50, v173
	v_mov_b32_e32 v163, v158
	v_mul_f32_e32 v158, v51, v174
	v_mov_b32_e32 v170, v158
	v_mul_f32_e32 v158, 0xbfb8aa3b, v44
	v_exp_f32_e32 v171, v158
	v_cvt_pk_bf16_f32 v158, v140, v157
	v_cvt_pk_bf16_f32 v159, v159, v160
	v_cvt_pk_bf16_f32 v160, v161, v162
	v_cvt_pk_bf16_f32 v161, v163, v170
	global_store_dwordx4 v[130:131], v[158:161], off offset:256
	v_add_f32_e32 v140, 1.0, v171
	v_rcp_f32_e32 v162, v140
	v_mul_f32_e32 v160, 0xbfb8aa3b, v45
	v_exp_f32_e32 v160, v160
	v_lshl_add_u64 v[130:131], v[128:129], 0, s[16:17]
	v_add_f32_e32 v158, 1.0, v160
	v_rcp_f32_e32 v161, v158
	v_mul_f32_e32 v157, v44, v162
	v_mov_b32_e32 v140, v157
	v_mul_f32_e32 v162, 0xbfb8aa3b, v46
	v_exp_f32_e32 v162, v162
	s_nop 0
	v_add_f32_e32 v160, 1.0, v162
	v_rcp_f32_e32 v163, v160
	v_mul_f32_e32 v157, v45, v161
	v_mul_f32_e32 v161, 0xbfb8aa3b, v47
	v_exp_f32_e32 v161, v161
	s_nop 0
	v_add_f32_e32 v161, 1.0, v161
	v_rcp_f32_e32 v170, v161
	v_mul_f32_e32 v158, v46, v163
	v_mov_b32_e32 v159, v158
	v_mul_f32_e32 v163, 0xbfb8aa3b, v40
	v_exp_f32_e32 v163, v163
	s_nop 0
	v_add_f32_e32 v162, 1.0, v163
	v_rcp_f32_e32 v171, v162
	v_mul_f32_e32 v158, v47, v170
	v_mov_b32_e32 v160, v158
	v_mul_f32_e32 v170, 0xbfb8aa3b, v41
	v_exp_f32_e32 v170, v170
	s_nop 0
	v_add_f32_e32 v163, 1.0, v170
	v_rcp_f32_e32 v172, v163
	v_mul_f32_e32 v158, v40, v171
	v_mov_b32_e32 v161, v158
	v_mul_f32_e32 v171, 0xbfb8aa3b, v42
	v_exp_f32_e32 v171, v171
	s_nop 0
	v_add_f32_e32 v170, 1.0, v171
	v_rcp_f32_e32 v173, v170
	v_mul_f32_e32 v158, v41, v172
	v_mov_b32_e32 v162, v158
	v_mul_f32_e32 v172, 0xbfb8aa3b, v43
	v_exp_f32_e32 v172, v172
	s_nop 0
	v_add_f32_e32 v171, 1.0, v172
	v_rcp_f32_e32 v174, v171
	v_mul_f32_e32 v158, v42, v173
	v_mov_b32_e32 v163, v158
	v_mul_f32_e32 v158, v43, v174
	v_mov_b32_e32 v170, v158
	v_cvt_pk_bf16_f32 v158, v140, v157
	v_mul_f32_e32 v140, 0xbfb8aa3b, v36
	v_exp_f32_e32 v140, v140
	v_cvt_pk_bf16_f32 v159, v159, v160
	v_cvt_pk_bf16_f32 v160, v161, v162
	v_cvt_pk_bf16_f32 v161, v163, v170
	v_add_co_u32_e32 v162, vcc, s69, v128
	v_add_f32_e32 v140, 1.0, v140
	v_rcp_f32_e32 v170, v140
	v_addc_co_u32_e32 v163, vcc, 0, v129, vcc
	global_store_dwordx4 v[162:163], v[158:161], off
	v_mul_f32_e32 v162, 0xbfb8aa3b, v38
	v_exp_f32_e32 v162, v162
	v_mul_f32_e32 v160, 0xbfb8aa3b, v37
	v_exp_f32_e32 v160, v160
	s_nop 0
	v_add_f32_e32 v158, 1.0, v160
	v_rcp_f32_e32 v161, v158
	v_mul_f32_e32 v157, v36, v170
	v_mov_b32_e32 v140, v157
	v_add_f32_e32 v160, 1.0, v162
	v_rcp_f32_e32 v163, v160
	v_mul_f32_e32 v157, v37, v161
	v_mul_f32_e32 v161, 0xbfb8aa3b, v39
	v_exp_f32_e32 v161, v161
	s_nop 0
	v_add_f32_e32 v161, 1.0, v161
	v_rcp_f32_e32 v170, v161
	v_mul_f32_e32 v158, v38, v163
	v_mov_b32_e32 v159, v158
	v_mul_f32_e32 v163, 0xbfb8aa3b, v32
	v_exp_f32_e32 v163, v163
	s_nop 0
	v_add_f32_e32 v162, 1.0, v163
	v_rcp_f32_e32 v171, v162
	v_mul_f32_e32 v158, v39, v170
	v_mov_b32_e32 v160, v158
	v_mul_f32_e32 v170, 0xbfb8aa3b, v33
	v_exp_f32_e32 v170, v170
	s_nop 0
	v_add_f32_e32 v163, 1.0, v170
	v_rcp_f32_e32 v172, v163
	v_mul_f32_e32 v158, v32, v171
	v_mov_b32_e32 v161, v158
	v_mul_f32_e32 v171, 0xbfb8aa3b, v34
	v_exp_f32_e32 v171, v171
	s_nop 0
	v_add_f32_e32 v170, 1.0, v171
	v_rcp_f32_e32 v173, v170
	v_mul_f32_e32 v158, v33, v172
	v_mov_b32_e32 v162, v158
	v_mul_f32_e32 v172, 0xbfb8aa3b, v35
	v_exp_f32_e32 v172, v172
	s_nop 0
	v_add_f32_e32 v171, 1.0, v172
	v_rcp_f32_e32 v174, v171
	v_mul_f32_e32 v158, v34, v173
	v_mov_b32_e32 v163, v158
	v_mul_f32_e32 v158, v35, v174
	v_mov_b32_e32 v170, v158
	v_mul_f32_e32 v158, 0xbfb8aa3b, v28
	v_exp_f32_e32 v171, v158
	v_cvt_pk_bf16_f32 v158, v140, v157
	v_cvt_pk_bf16_f32 v159, v159, v160
	v_cvt_pk_bf16_f32 v160, v161, v162
	v_cvt_pk_bf16_f32 v161, v163, v170
	global_store_dwordx4 v[130:131], v[158:161], off offset:256
	v_add_f32_e32 v140, 1.0, v171
	v_rcp_f32_e32 v162, v140
	v_mul_f32_e32 v160, 0xbfb8aa3b, v29
	v_exp_f32_e32 v160, v160
	v_lshl_add_u64 v[130:131], v[128:129], 0, s[18:19]
	v_add_f32_e32 v158, 1.0, v160
	v_rcp_f32_e32 v161, v158
	v_mul_f32_e32 v157, v28, v162
	v_mov_b32_e32 v140, v157
	v_mul_f32_e32 v162, 0xbfb8aa3b, v30
	v_exp_f32_e32 v162, v162
	s_nop 0
	v_add_f32_e32 v160, 1.0, v162
	v_rcp_f32_e32 v163, v160
	v_mul_f32_e32 v157, v29, v161
	v_mul_f32_e32 v161, 0xbfb8aa3b, v31
	v_exp_f32_e32 v161, v161
	s_nop 0
	v_add_f32_e32 v161, 1.0, v161
	v_rcp_f32_e32 v170, v161
	v_mul_f32_e32 v158, v30, v163
	v_mov_b32_e32 v159, v158
	v_mul_f32_e32 v163, 0xbfb8aa3b, v24
	v_exp_f32_e32 v163, v163
	s_nop 0
	v_add_f32_e32 v162, 1.0, v163
	v_rcp_f32_e32 v171, v162
	v_mul_f32_e32 v158, v31, v170
	v_mov_b32_e32 v160, v158
	v_mul_f32_e32 v170, 0xbfb8aa3b, v25
	v_exp_f32_e32 v170, v170
	s_nop 0
	v_add_f32_e32 v163, 1.0, v170
	v_rcp_f32_e32 v172, v163
	v_mul_f32_e32 v158, v24, v171
	v_mov_b32_e32 v161, v158
	v_mul_f32_e32 v171, 0xbfb8aa3b, v26
	v_exp_f32_e32 v171, v171
	s_nop 0
	v_add_f32_e32 v170, 1.0, v171
	v_rcp_f32_e32 v173, v170
	v_mul_f32_e32 v158, v25, v172
	v_mov_b32_e32 v162, v158
	v_mul_f32_e32 v172, 0xbfb8aa3b, v27
	v_exp_f32_e32 v172, v172
	s_nop 0
; __device__ __forceinline__ f32x4 silu4(f32x4 v) { f32x4 o; o[0] = silu_f(v[0]); o[1] = silu_f(v[1]); o[2] = silu_f(v[2]); o[3] = silu_f(v[3]); return o; }
; __device__ __forceinline__ float silu_f(float v) { return v / (1.0f + __expf(-v)); }
;     __device__ __forceinline__ void operator()(const f32x4 (&acc)[2][2][4][2], const Unit& u, int wr, int wc, int fr, int fq) const {
;     ...
;         } else if (u.pn < 12) {
;             bf16_t* base = SG1 + (u.pn - 4) * 256 + cl;
; #pragma unroll
;             for (int ai = 0; ai < 2; ++ai)
; #pragma unroll
;                 for (int m = 0; m < 4; ++m) { bf16_t* rowp = base + (size_t)(row0 + ai * HALF + m * 16) * 2048;
; #pragma unroll
;                     for (int bj = 0; bj < 2; ++bj) st8(rowp + bj * HALF, silu4(acc[ai][bj][m][0]), silu4(acc[ai][bj][m][1])); }
	v_add_f32_e32 v171, 1.0, v172
	v_rcp_f32_e32 v174, v171
	v_mul_f32_e32 v158, v26, v173
	v_mov_b32_e32 v163, v158
	v_mul_f32_e32 v158, v27, v174
	v_mov_b32_e32 v170, v158
	v_cvt_pk_bf16_f32 v158, v140, v157
	v_mul_f32_e32 v140, 0xbfb8aa3b, v20
	v_exp_f32_e32 v140, v140
	v_cvt_pk_bf16_f32 v159, v159, v160
	v_cvt_pk_bf16_f32 v160, v161, v162
	v_cvt_pk_bf16_f32 v161, v163, v170
	v_add_co_u32_e32 v162, vcc, s70, v128
	v_add_f32_e32 v140, 1.0, v140
	v_rcp_f32_e32 v170, v140
	v_addc_co_u32_e32 v163, vcc, 0, v129, vcc
	global_store_dwordx4 v[162:163], v[158:161], off
	v_mul_f32_e32 v162, 0xbfb8aa3b, v22
	v_exp_f32_e32 v162, v162
	v_mul_f32_e32 v160, 0xbfb8aa3b, v21
	v_exp_f32_e32 v160, v160
	s_nop 0
	v_add_f32_e32 v158, 1.0, v160
	v_rcp_f32_e32 v161, v158
	v_mul_f32_e32 v157, v20, v170
	v_mov_b32_e32 v140, v157
	v_add_f32_e32 v160, 1.0, v162
	v_rcp_f32_e32 v163, v160
	v_mul_f32_e32 v157, v21, v161
	v_mul_f32_e32 v161, 0xbfb8aa3b, v23
	v_exp_f32_e32 v161, v161
	s_nop 0
	v_add_f32_e32 v161, 1.0, v161
	v_rcp_f32_e32 v170, v161
	v_mul_f32_e32 v158, v22, v163
	v_mov_b32_e32 v159, v158
	v_mul_f32_e32 v163, 0xbfb8aa3b, v16
	v_exp_f32_e32 v163, v163
	s_nop 0
	v_add_f32_e32 v162, 1.0, v163
	v_rcp_f32_e32 v171, v162
	v_mul_f32_e32 v158, v23, v170
	v_mov_b32_e32 v160, v158
	v_mul_f32_e32 v170, 0xbfb8aa3b, v17
	v_exp_f32_e32 v170, v170
	s_nop 0
	v_add_f32_e32 v163, 1.0, v170
	v_rcp_f32_e32 v172, v163
	v_mul_f32_e32 v158, v16, v171
	v_mov_b32_e32 v161, v158
	v_mul_f32_e32 v171, 0xbfb8aa3b, v18
	v_exp_f32_e32 v171, v171
	s_nop 0
	v_add_f32_e32 v170, 1.0, v171
	v_rcp_f32_e32 v173, v170
	v_mul_f32_e32 v158, v17, v172
	v_mov_b32_e32 v162, v158
	v_mul_f32_e32 v172, 0xbfb8aa3b, v19
	v_exp_f32_e32 v172, v172
	s_nop 0
	v_add_f32_e32 v171, 1.0, v172
	v_rcp_f32_e32 v174, v171
	v_mul_f32_e32 v158, v18, v173
	v_mov_b32_e32 v163, v158
	v_mul_f32_e32 v158, v19, v174
	v_mov_b32_e32 v170, v158
	v_mul_f32_e32 v158, 0xbfb8aa3b, v12
	v_exp_f32_e32 v171, v158
	v_cvt_pk_bf16_f32 v158, v140, v157
	v_cvt_pk_bf16_f32 v159, v159, v160
	v_cvt_pk_bf16_f32 v160, v161, v162
	v_cvt_pk_bf16_f32 v161, v163, v170
	global_store_dwordx4 v[130:131], v[158:161], off offset:256
	v_add_f32_e32 v140, 1.0, v171
	v_rcp_f32_e32 v162, v140
	v_mul_f32_e32 v160, 0xbfb8aa3b, v13
	v_exp_f32_e32 v160, v160
	v_lshl_add_u64 v[130:131], v[128:129], 0, s[20:21]
	v_add_f32_e32 v158, 1.0, v160
	v_rcp_f32_e32 v161, v158
	v_mul_f32_e32 v157, v12, v162
	v_mov_b32_e32 v140, v157
	v_mul_f32_e32 v162, 0xbfb8aa3b, v14
	v_exp_f32_e32 v162, v162
	s_nop 0
	v_add_f32_e32 v160, 1.0, v162
	v_rcp_f32_e32 v163, v160
	v_mul_f32_e32 v157, v13, v161
	v_mul_f32_e32 v161, 0xbfb8aa3b, v15
	v_exp_f32_e32 v161, v161
	s_nop 0
	v_add_f32_e32 v161, 1.0, v161
	v_rcp_f32_e32 v170, v161
	v_mul_f32_e32 v158, v14, v163
	v_mov_b32_e32 v159, v158
	v_mul_f32_e32 v163, 0xbfb8aa3b, v8
	v_exp_f32_e32 v163, v163
	s_nop 0
	v_add_f32_e32 v162, 1.0, v163
	v_rcp_f32_e32 v171, v162
	v_mul_f32_e32 v158, v15, v170
	v_mov_b32_e32 v160, v158
	v_mul_f32_e32 v170, 0xbfb8aa3b, v9
	v_exp_f32_e32 v170, v170
	s_nop 0
	v_add_f32_e32 v163, 1.0, v170
	v_rcp_f32_e32 v172, v163
	v_mul_f32_e32 v158, v8, v171
	v_mov_b32_e32 v161, v158
	v_mul_f32_e32 v171, 0xbfb8aa3b, v10
	v_exp_f32_e32 v171, v171
	s_nop 0
	v_add_f32_e32 v170, 1.0, v171
	v_rcp_f32_e32 v173, v170
	v_mul_f32_e32 v158, v9, v172
	v_mov_b32_e32 v162, v158
	v_mul_f32_e32 v172, 0xbfb8aa3b, v11
	v_exp_f32_e32 v172, v172
	s_nop 0
	v_add_f32_e32 v171, 1.0, v172
	v_rcp_f32_e32 v174, v171
	v_mul_f32_e32 v158, v10, v173
	v_mov_b32_e32 v163, v158
	v_mul_f32_e32 v158, v11, v174
	v_mov_b32_e32 v170, v158
	v_cvt_pk_bf16_f32 v158, v140, v157
	v_mul_f32_e32 v140, 0xbfb8aa3b, v4
	v_exp_f32_e32 v140, v140
	v_cvt_pk_bf16_f32 v159, v159, v160
	v_cvt_pk_bf16_f32 v160, v161, v162
	v_add_co_u32_e32 v128, vcc, s71, v128
	v_add_f32_e32 v140, 1.0, v140
	v_rcp_f32_e32 v162, v140
	v_addc_co_u32_e32 v129, vcc, 0, v129, vcc
	v_cvt_pk_bf16_f32 v161, v163, v170
	global_store_dwordx4 v[128:129], v[158:161], off
	s_nop 1
	v_mul_f32_e32 v158, 0xbfb8aa3b, v5
	v_exp_f32_e32 v158, v158
	s_nop 0
	v_add_f32_e32 v157, 1.0, v158
	v_rcp_f32_e32 v159, v157
	v_mul_f32_e32 v128, v4, v162
	v_mul_f32_e32 v160, 0xbfb8aa3b, v6
	v_exp_f32_e32 v160, v160
	s_nop 0
	v_add_f32_e32 v158, 1.0, v160
	v_rcp_f32_e32 v161, v158
	v_mul_f32_e32 v129, v5, v159
	v_mul_f32_e32 v159, 0xbfb8aa3b, v7
	v_exp_f32_e32 v159, v159
	s_nop 0
	v_add_f32_e32 v159, 1.0, v159
	v_rcp_f32_e32 v162, v159
	v_mul_f32_e32 v140, v6, v161
	v_mul_f32_e32 v161, 0xbfb8aa3b, v0
	v_exp_f32_e32 v161, v161
	s_nop 0
	v_add_f32_e32 v160, 1.0, v161
	v_rcp_f32_e32 v163, v160
	v_mul_f32_e32 v157, v7, v162
	v_mul_f32_e32 v162, 0xbfb8aa3b, v1
	v_exp_f32_e32 v162, v162
	s_nop 0
	v_add_f32_e32 v161, 1.0, v162
	v_rcp_f32_e32 v170, v161
	v_mul_f32_e32 v158, v0, v163
	v_mov_b32_e32 v160, v158
	v_mul_f32_e32 v163, 0xbfb8aa3b, v2
	v_exp_f32_e32 v163, v163
	s_nop 0
	v_add_f32_e32 v162, 1.0, v163
	v_rcp_f32_e32 v171, v162
	v_mul_f32_e32 v158, v1, v170
	v_mov_b32_e32 v161, v158
	v_mul_f32_e32 v170, 0xbfb8aa3b, v3
	v_exp_f32_e32 v170, v170
	s_nop 0
	v_add_f32_e32 v163, 1.0, v170
	v_rcp_f32_e32 v172, v163
	v_mul_f32_e32 v158, v2, v171
	v_mov_b32_e32 v162, v158
	v_mul_f32_e32 v158, v3, v172
	v_mov_b32_e32 v163, v158
	v_cvt_pk_bf16_f32 v158, v128, v129
	v_cvt_pk_bf16_f32 v159, v140, v157
	v_cvt_pk_bf16_f32 v160, v160, v161
	v_cvt_pk_bf16_f32 v161, v162, v163
	global_store_dwordx4 v[130:131], v[158:161], off offset:256
